# v14 combo + software-pipelined residual epilogues (W_out and FFN-down): x_in loads prefetched 4 units ahead, waits counted on loads only
# speedup vs baseline: 1.0122x; 1.0049x over previous
; __device__ __forceinline__ unsigned pk2(float lo, float hi) { const f32v2_t v = {lo, hi}; const bf16v2_t b = __builtin_convertvector(v, bf16v2_t); return __builtin_bit_cast(unsigned, b); }
; #define ST_OUT2(p, v) __builtin_nontemporal_store((v), (p))
;     __device__ __forceinline__ void operator()(AccRef acc, const Unit& u, int wr, int wc, int fr, int fq) const {
;         const int row0 = u.pm * BM + wr * 64 + fr, col0 = u.pn * BM + wc * 32 + 8 * fq;
; #pragma unroll
;         for (int ai = 0; ai < 2; ++ai)
; #pragma unroll
;             for (int m = 0; m < 4; ++m) {
;                 const int row = row0 + ai * HALF + m * 16;
;                 float ss = 0.f;
; #pragma unroll
;                 for (int bj = 0; bj < 2; ++bj) {
;                     const size_t off = (size_t)row * DM + col0 + bj * HALF;
;                     f32x4 x0 = *(const f32x4*)(xin + off), x1 = *(const f32x4*)(xin + off + 4);
;                     x0 = x0 + acc[ai][bj][m][0] * scale; x1 = x1 + acc[ai][bj][m][1] * scale;
;                     ST_OUT2((f32x4*)(xout + off), x0); ST_OUT2((f32x4*)(xout + off + 4), x1);
;                     u32x4 o; o.x = pk2(x0[0], x0[1]); o.y = pk2(x0[2], x0[3]); o.z = pk2(x1[0], x1[1]); o.w = pk2(x1[2], x1[3]);
;                     if (wxb) ST_OUT2((u32x4*)(XB + off), o);
;                     ss += x0[0] * x0[0] + x0[1] * x0[1] + x0[2] * x0[2] + x0[3] * x0[3] + x1[0] * x1[0] + x1[1] * x1[1] + x1[2] * x1[2] + x1[3] * x1[3];
;                 }
;                 ss += __shfl_xor(ss, 16); ss += __shfl_xor(ss, 32);
;                 if (fq == 0) atomicAdd(rssn + row, (unsigned long long)(ss * 16777216.f));
;             }
.LBB0_101:
	v_lshl_add_u32 v156, s20, 8, v164
	v_lshl_or_b32 v160, s60, 8, v166
	v_ashrrev_i32_e32 v157, 31, v156
	v_ashrrev_i32_e32 v161, 31, v160
	v_lshlrev_b64 v[158:159], 11, v[156:157]
	v_lshl_add_u64 v[158:159], v[158:159], 0, v[160:161]
	v_lshl_add_u64 v[194:195], v[158:159], 2, s[80:81]
	v_lshl_add_u64 v[196:197], v[158:159], 2, s[80:81]
	v_lshl_add_u64 v[198:199], v[158:159], 1, s[90:91]
	v_lshl_add_u64 v[200:201], v[156:157], 3, s[42:43]
	v_and_b32_e32 v204, 64, v177
	v_add_u32_e32 v204, 64, v204
	v_xor_b32_e32 v202, 16, v177
	v_xor_b32_e32 v203, 32, v177
	v_cmp_lt_i32_e32 vcc, v202, v204
	s_nop 1
	v_cndmask_b32_e32 v202, v177, v202, vcc
	v_cmp_lt_i32_e32 vcc, v203, v204
	s_nop 1
	v_cndmask_b32_e32 v203, v177, v203, vcc
	v_lshlrev_b32_e32 v202, 2, v202
	v_lshlrev_b32_e32 v203, 2, v203
	s_mov_b32 s101, 0
	s_mov_b32 s100, 0x0
	v_lshl_add_u64 v[204:205], v[194:195], 0, s[100:101]
	global_load_dwordx4 v[206:209], v[204:205], off
	global_load_dwordx4 v[210:213], v[204:205], off offset:16
	s_mov_b32 s100, 0x0
	v_lshl_add_u64 v[204:205], v[194:195], 0, s[100:101]
	global_load_dwordx4 v[214:217], v[204:205], off offset:512
	global_load_dwordx4 v[218:221], v[204:205], off offset:528
	s_mov_b32 s100, 0x20000
	v_lshl_add_u64 v[204:205], v[194:195], 0, s[100:101]
	global_load_dwordx4 v[222:225], v[204:205], off
	global_load_dwordx4 v[226:229], v[204:205], off offset:16
	s_mov_b32 s100, 0x20000
	v_lshl_add_u64 v[204:205], v[194:195], 0, s[100:101]
	global_load_dwordx4 v[230:233], v[204:205], off offset:512
	global_load_dwordx4 v[234:237], v[204:205], off offset:528
	s_waitcnt vmcnt(6)
	v_pk_add_f32 v[124:125], v[124:125], v[206:207]
	v_pk_add_f32 v[126:127], v[126:127], v[208:209]
	v_pk_add_f32 v[120:121], v[120:121], v[210:211]
	v_pk_add_f32 v[122:123], v[122:123], v[212:213]
	s_mov_b32 s100, 0x0
	v_lshl_add_u64 v[182:183], v[196:197], 0, s[100:101]
	global_store_dwordx4 v[182:183], v[124:127], off
	global_store_dwordx4 v[182:183], v[120:123], off offset:16
	v_cvt_pk_bf16_f32 v186, v124, v125
	v_cvt_pk_bf16_f32 v187, v126, v127
	v_cvt_pk_bf16_f32 v188, v120, v121
	v_cvt_pk_bf16_f32 v189, v122, v123
	s_mov_b32 s100, 0x0
	v_lshl_add_u64 v[184:185], v[198:199], 0, s[100:101]
	global_store_dwordx4 v[184:185], v[186:189], off
	v_mul_f32_e32 v170, v125, v125
	v_fmac_f32_e32 v170, v124, v124
	v_fmac_f32_e32 v170, v126, v126
	v_fmac_f32_e32 v170, v127, v127
	v_fmac_f32_e32 v170, v120, v120
	v_fmac_f32_e32 v170, v121, v121
	v_fmac_f32_e32 v170, v122, v122
	v_fmac_f32_e32 v170, v123, v123
	s_mov_b32 s100, 0x40000
	v_lshl_add_u64 v[204:205], v[194:195], 0, s[100:101]
	global_load_dwordx4 v[206:209], v[204:205], off
	global_load_dwordx4 v[210:213], v[204:205], off offset:16
	s_waitcnt vmcnt(6)
	v_pk_add_f32 v[116:117], v[116:117], v[214:215]
	v_pk_add_f32 v[118:119], v[118:119], v[216:217]
	v_pk_add_f32 v[112:113], v[112:113], v[218:219]
	v_pk_add_f32 v[114:115], v[114:115], v[220:221]
	s_mov_b32 s100, 0x0
	v_lshl_add_u64 v[182:183], v[196:197], 0, s[100:101]
	global_store_dwordx4 v[182:183], v[116:119], off offset:512
	global_store_dwordx4 v[182:183], v[112:115], off offset:528
	v_cvt_pk_bf16_f32 v186, v116, v117
	v_cvt_pk_bf16_f32 v187, v118, v119
	v_cvt_pk_bf16_f32 v188, v112, v113
	v_cvt_pk_bf16_f32 v189, v114, v115
	s_mov_b32 s100, 0x0
	v_lshl_add_u64 v[184:185], v[198:199], 0, s[100:101]
	global_store_dwordx4 v[184:185], v[186:189], off offset:256
	v_mul_f32_e32 v171, v117, v117
	v_fmac_f32_e32 v171, v116, v116
	v_fmac_f32_e32 v171, v118, v118
	v_fmac_f32_e32 v171, v119, v119
	v_fmac_f32_e32 v171, v112, v112
	v_fmac_f32_e32 v171, v113, v113
	v_fmac_f32_e32 v171, v114, v114
	v_fmac_f32_e32 v171, v115, v115
	v_add_f32_e32 v170, v170, v171
	ds_bpermute_b32 v163, v202, v170
	s_waitcnt lgkmcnt(0)
	v_add_f32_e32 v170, v170, v163
	ds_bpermute_b32 v163, v203, v170
	s_and_saveexec_b64 s[22:23], s[38:39]
	s_waitcnt lgkmcnt(0)
	v_add_f32_e32 v170, v170, v163
	v_mul_f32_e32 v170, 0x4b800000, v170
	v_trunc_f32_e32 v170, v170
	v_mul_f32_e32 v163, 0x2f800000, v170
	v_floor_f32_e32 v163, v163
	v_fmac_f32_e32 v170, 0xcf800000, v163
	v_cvt_u32_f32_e32 v172, v170
	v_cvt_u32_f32_e32 v173, v163
	s_mov_b32 s100, 0x0
	v_lshl_add_u64 v[184:185], v[200:201], 0, s[100:101]
	global_atomic_add_x2 v[184:185], v[172:173], off
	s_or_b64 exec, exec, s[22:23]
	s_mov_b32 s100, 0x40000
	v_lshl_add_u64 v[204:205], v[194:195], 0, s[100:101]
	global_load_dwordx4 v[214:217], v[204:205], off offset:512
	global_load_dwordx4 v[218:221], v[204:205], off offset:528
	s_waitcnt vmcnt(6)
	v_pk_add_f32 v[108:109], v[108:109], v[222:223]
	v_pk_add_f32 v[110:111], v[110:111], v[224:225]
	v_pk_add_f32 v[104:105], v[104:105], v[226:227]
	v_pk_add_f32 v[106:107], v[106:107], v[228:229]
	s_mov_b32 s100, 0x20000
	v_lshl_add_u64 v[182:183], v[196:197], 0, s[100:101]
	global_store_dwordx4 v[182:183], v[108:111], off
	global_store_dwordx4 v[182:183], v[104:107], off offset:16
	v_cvt_pk_bf16_f32 v186, v108, v109
	v_cvt_pk_bf16_f32 v187, v110, v111
	v_cvt_pk_bf16_f32 v188, v104, v105
	v_cvt_pk_bf16_f32 v189, v106, v107
	s_mov_b32 s100, 0x10000
	v_lshl_add_u64 v[184:185], v[198:199], 0, s[100:101]
	global_store_dwordx4 v[184:185], v[186:189], off
	v_mul_f32_e32 v170, v109, v109
	v_fmac_f32_e32 v170, v108, v108
	v_fmac_f32_e32 v170, v110, v110
	v_fmac_f32_e32 v170, v111, v111
	v_fmac_f32_e32 v170, v104, v104
	v_fmac_f32_e32 v170, v105, v105
	v_fmac_f32_e32 v170, v106, v106
	v_fmac_f32_e32 v170, v107, v107
	s_mov_b32 s100, 0x60000
	v_lshl_add_u64 v[204:205], v[194:195], 0, s[100:101]
	global_load_dwordx4 v[222:225], v[204:205], off
	global_load_dwordx4 v[226:229], v[204:205], off offset:16
	s_waitcnt vmcnt(6)
; __device__ __forceinline__ unsigned pk2(float lo, float hi) { const f32v2_t v = {lo, hi}; const bf16v2_t b = __builtin_convertvector(v, bf16v2_t); return __builtin_bit_cast(unsigned, b); }
; #define ST_OUT2(p, v) __builtin_nontemporal_store((v), (p))
;     __device__ __forceinline__ void operator()(AccRef acc, const Unit& u, int wr, int wc, int fr, int fq) const {
;     ...
;                 const int row = row0 + ai * HALF + m * 16;
;                 float ss = 0.f;
; #pragma unroll
;                 for (int bj = 0; bj < 2; ++bj) {
;                     const size_t off = (size_t)row * DM + col0 + bj * HALF;
;                     f32x4 x0 = *(const f32x4*)(xin + off), x1 = *(const f32x4*)(xin + off + 4);
;                     x0 = x0 + acc[ai][bj][m][0] * scale; x1 = x1 + acc[ai][bj][m][1] * scale;
;                     ST_OUT2((f32x4*)(xout + off), x0); ST_OUT2((f32x4*)(xout + off + 4), x1);
;                     u32x4 o; o.x = pk2(x0[0], x0[1]); o.y = pk2(x0[2], x0[3]); o.z = pk2(x1[0], x1[1]); o.w = pk2(x1[2], x1[3]);
;                     if (wxb) ST_OUT2((u32x4*)(XB + off), o);
;                     ss += x0[0] * x0[0] + x0[1] * x0[1] + x0[2] * x0[2] + x0[3] * x0[3] + x1[0] * x1[0] + x1[1] * x1[1] + x1[2] * x1[2] + x1[3] * x1[3];
;                 }
;                 ss += __shfl_xor(ss, 16); ss += __shfl_xor(ss, 32);
;                 if (fq == 0) atomicAdd(rssn + row, (unsigned long long)(ss * 16777216.f));
;             }
	v_pk_add_f32 v[100:101], v[100:101], v[230:231]
	v_pk_add_f32 v[102:103], v[102:103], v[232:233]
	v_pk_add_f32 v[96:97], v[96:97], v[234:235]
	v_pk_add_f32 v[98:99], v[98:99], v[236:237]
	s_mov_b32 s100, 0x20000
	v_lshl_add_u64 v[182:183], v[196:197], 0, s[100:101]
	global_store_dwordx4 v[182:183], v[100:103], off offset:512
	global_store_dwordx4 v[182:183], v[96:99], off offset:528
	v_cvt_pk_bf16_f32 v186, v100, v101
	v_cvt_pk_bf16_f32 v187, v102, v103
	v_cvt_pk_bf16_f32 v188, v96, v97
	v_cvt_pk_bf16_f32 v189, v98, v99
	s_mov_b32 s100, 0x10000
	v_lshl_add_u64 v[184:185], v[198:199], 0, s[100:101]
	global_store_dwordx4 v[184:185], v[186:189], off offset:256
	v_mul_f32_e32 v171, v101, v101
	v_fmac_f32_e32 v171, v100, v100
	v_fmac_f32_e32 v171, v102, v102
	v_fmac_f32_e32 v171, v103, v103
	v_fmac_f32_e32 v171, v96, v96
	v_fmac_f32_e32 v171, v97, v97
	v_fmac_f32_e32 v171, v98, v98
	v_fmac_f32_e32 v171, v99, v99
	v_add_f32_e32 v170, v170, v171
	ds_bpermute_b32 v163, v202, v170
	s_waitcnt lgkmcnt(0)
	v_add_f32_e32 v170, v170, v163
	ds_bpermute_b32 v163, v203, v170
	s_and_saveexec_b64 s[22:23], s[38:39]
	s_waitcnt lgkmcnt(0)
	v_add_f32_e32 v170, v170, v163
	v_mul_f32_e32 v170, 0x4b800000, v170
	v_trunc_f32_e32 v170, v170
	v_mul_f32_e32 v163, 0x2f800000, v170
	v_floor_f32_e32 v163, v163
	v_fmac_f32_e32 v170, 0xcf800000, v163
	v_cvt_u32_f32_e32 v172, v170
	v_cvt_u32_f32_e32 v173, v163
	s_mov_b32 s100, 0x80
	v_lshl_add_u64 v[184:185], v[200:201], 0, s[100:101]
	global_atomic_add_x2 v[184:185], v[172:173], off
	s_or_b64 exec, exec, s[22:23]
	s_mov_b32 s100, 0x60000
	v_lshl_add_u64 v[204:205], v[194:195], 0, s[100:101]
	global_load_dwordx4 v[230:233], v[204:205], off offset:512
	global_load_dwordx4 v[234:237], v[204:205], off offset:528
	s_waitcnt vmcnt(6)
	v_pk_add_f32 v[92:93], v[92:93], v[206:207]
	v_pk_add_f32 v[94:95], v[94:95], v[208:209]
	v_pk_add_f32 v[88:89], v[88:89], v[210:211]
	v_pk_add_f32 v[90:91], v[90:91], v[212:213]
	s_mov_b32 s100, 0x40000
	v_lshl_add_u64 v[182:183], v[196:197], 0, s[100:101]
	global_store_dwordx4 v[182:183], v[92:95], off
	global_store_dwordx4 v[182:183], v[88:91], off offset:16
	v_cvt_pk_bf16_f32 v186, v92, v93
	v_cvt_pk_bf16_f32 v187, v94, v95
	v_cvt_pk_bf16_f32 v188, v88, v89
	v_cvt_pk_bf16_f32 v189, v90, v91
	s_mov_b32 s100, 0x20000
	v_lshl_add_u64 v[184:185], v[198:199], 0, s[100:101]
	global_store_dwordx4 v[184:185], v[186:189], off
	v_mul_f32_e32 v170, v93, v93
	v_fmac_f32_e32 v170, v92, v92
	v_fmac_f32_e32 v170, v94, v94
	v_fmac_f32_e32 v170, v95, v95
	v_fmac_f32_e32 v170, v88, v88
	v_fmac_f32_e32 v170, v89, v89
	v_fmac_f32_e32 v170, v90, v90
	v_fmac_f32_e32 v170, v91, v91
	s_mov_b32 s100, 0x100000
	v_lshl_add_u64 v[204:205], v[194:195], 0, s[100:101]
	global_load_dwordx4 v[206:209], v[204:205], off
	global_load_dwordx4 v[210:213], v[204:205], off offset:16
	s_waitcnt vmcnt(6)
	v_pk_add_f32 v[84:85], v[84:85], v[214:215]
	v_pk_add_f32 v[86:87], v[86:87], v[216:217]
	v_pk_add_f32 v[80:81], v[80:81], v[218:219]
	v_pk_add_f32 v[82:83], v[82:83], v[220:221]
	s_mov_b32 s100, 0x40000
	v_lshl_add_u64 v[182:183], v[196:197], 0, s[100:101]
	global_store_dwordx4 v[182:183], v[84:87], off offset:512
	global_store_dwordx4 v[182:183], v[80:83], off offset:528
	v_cvt_pk_bf16_f32 v186, v84, v85
	v_cvt_pk_bf16_f32 v187, v86, v87
	v_cvt_pk_bf16_f32 v188, v80, v81
	v_cvt_pk_bf16_f32 v189, v82, v83
	s_mov_b32 s100, 0x20000
	v_lshl_add_u64 v[184:185], v[198:199], 0, s[100:101]
	global_store_dwordx4 v[184:185], v[186:189], off offset:256
	v_mul_f32_e32 v171, v85, v85
	v_fmac_f32_e32 v171, v84, v84
	v_fmac_f32_e32 v171, v86, v86
	v_fmac_f32_e32 v171, v87, v87
	v_fmac_f32_e32 v171, v80, v80
	v_fmac_f32_e32 v171, v81, v81
	v_fmac_f32_e32 v171, v82, v82
	v_fmac_f32_e32 v171, v83, v83
	v_add_f32_e32 v170, v170, v171
	ds_bpermute_b32 v163, v202, v170
	s_waitcnt lgkmcnt(0)
	v_add_f32_e32 v170, v170, v163
	ds_bpermute_b32 v163, v203, v170
	s_and_saveexec_b64 s[22:23], s[38:39]
	s_waitcnt lgkmcnt(0)
	v_add_f32_e32 v170, v170, v163
	v_mul_f32_e32 v170, 0x4b800000, v170
	v_trunc_f32_e32 v170, v170
	v_mul_f32_e32 v163, 0x2f800000, v170
	v_floor_f32_e32 v163, v163
	v_fmac_f32_e32 v170, 0xcf800000, v163
	v_cvt_u32_f32_e32 v172, v170
	v_cvt_u32_f32_e32 v173, v163
	s_mov_b32 s100, 0x100
	v_lshl_add_u64 v[184:185], v[200:201], 0, s[100:101]
	global_atomic_add_x2 v[184:185], v[172:173], off
	s_or_b64 exec, exec, s[22:23]
	s_mov_b32 s100, 0x100000
	v_lshl_add_u64 v[204:205], v[194:195], 0, s[100:101]
	global_load_dwordx4 v[214:217], v[204:205], off offset:512
	global_load_dwordx4 v[218:221], v[204:205], off offset:528
	s_waitcnt vmcnt(6)
	v_pk_add_f32 v[76:77], v[76:77], v[222:223]
	v_pk_add_f32 v[78:79], v[78:79], v[224:225]
	v_pk_add_f32 v[72:73], v[72:73], v[226:227]
	v_pk_add_f32 v[74:75], v[74:75], v[228:229]
	s_mov_b32 s100, 0x60000
	v_lshl_add_u64 v[182:183], v[196:197], 0, s[100:101]
	global_store_dwordx4 v[182:183], v[76:79], off
	global_store_dwordx4 v[182:183], v[72:75], off offset:16
	v_cvt_pk_bf16_f32 v186, v76, v77
	v_cvt_pk_bf16_f32 v187, v78, v79
	v_cvt_pk_bf16_f32 v188, v72, v73
	v_cvt_pk_bf16_f32 v189, v74, v75
	s_mov_b32 s100, 0x30000
	v_lshl_add_u64 v[184:185], v[198:199], 0, s[100:101]
	global_store_dwordx4 v[184:185], v[186:189], off
	v_mul_f32_e32 v170, v77, v77
	v_fmac_f32_e32 v170, v76, v76
	v_fmac_f32_e32 v170, v78, v78
	v_fmac_f32_e32 v170, v79, v79
	v_fmac_f32_e32 v170, v72, v72
	v_fmac_f32_e32 v170, v73, v73
	v_fmac_f32_e32 v170, v74, v74
	v_fmac_f32_e32 v170, v75, v75
	s_mov_b32 s100, 0x120000
	v_lshl_add_u64 v[204:205], v[194:195], 0, s[100:101]
	global_load_dwordx4 v[222:225], v[204:205], off
	global_load_dwordx4 v[226:229], v[204:205], off offset:16
	s_waitcnt vmcnt(6)
; __device__ __forceinline__ unsigned pk2(float lo, float hi) { const f32v2_t v = {lo, hi}; const bf16v2_t b = __builtin_convertvector(v, bf16v2_t); return __builtin_bit_cast(unsigned, b); }
; #define ST_OUT2(p, v) __builtin_nontemporal_store((v), (p))
;     __device__ __forceinline__ void operator()(AccRef acc, const Unit& u, int wr, int wc, int fr, int fq) const {
;     ...
;                 const int row = row0 + ai * HALF + m * 16;
;                 float ss = 0.f;
; #pragma unroll
;                 for (int bj = 0; bj < 2; ++bj) {
;                     const size_t off = (size_t)row * DM + col0 + bj * HALF;
;                     f32x4 x0 = *(const f32x4*)(xin + off), x1 = *(const f32x4*)(xin + off + 4);
;                     x0 = x0 + acc[ai][bj][m][0] * scale; x1 = x1 + acc[ai][bj][m][1] * scale;
;                     ST_OUT2((f32x4*)(xout + off), x0); ST_OUT2((f32x4*)(xout + off + 4), x1);
;                     u32x4 o; o.x = pk2(x0[0], x0[1]); o.y = pk2(x0[2], x0[3]); o.z = pk2(x1[0], x1[1]); o.w = pk2(x1[2], x1[3]);
;                     if (wxb) ST_OUT2((u32x4*)(XB + off), o);
;                     ss += x0[0] * x0[0] + x0[1] * x0[1] + x0[2] * x0[2] + x0[3] * x0[3] + x1[0] * x1[0] + x1[1] * x1[1] + x1[2] * x1[2] + x1[3] * x1[3];
;                 }
;                 ss += __shfl_xor(ss, 16); ss += __shfl_xor(ss, 32);
;                 if (fq == 0) atomicAdd(rssn + row, (unsigned long long)(ss * 16777216.f));
;             }
	v_pk_add_f32 v[68:69], v[68:69], v[230:231]
	v_pk_add_f32 v[70:71], v[70:71], v[232:233]
	v_pk_add_f32 v[64:65], v[64:65], v[234:235]
	v_pk_add_f32 v[66:67], v[66:67], v[236:237]
	s_mov_b32 s100, 0x60000
	v_lshl_add_u64 v[182:183], v[196:197], 0, s[100:101]
	global_store_dwordx4 v[182:183], v[68:71], off offset:512
	global_store_dwordx4 v[182:183], v[64:67], off offset:528
	v_cvt_pk_bf16_f32 v186, v68, v69
	v_cvt_pk_bf16_f32 v187, v70, v71
	v_cvt_pk_bf16_f32 v188, v64, v65
	v_cvt_pk_bf16_f32 v189, v66, v67
	s_mov_b32 s100, 0x30000
	v_lshl_add_u64 v[184:185], v[198:199], 0, s[100:101]
	global_store_dwordx4 v[184:185], v[186:189], off offset:256
	v_mul_f32_e32 v171, v69, v69
	v_fmac_f32_e32 v171, v68, v68
	v_fmac_f32_e32 v171, v70, v70
	v_fmac_f32_e32 v171, v71, v71
	v_fmac_f32_e32 v171, v64, v64
	v_fmac_f32_e32 v171, v65, v65
	v_fmac_f32_e32 v171, v66, v66
	v_fmac_f32_e32 v171, v67, v67
	v_add_f32_e32 v170, v170, v171
	ds_bpermute_b32 v163, v202, v170
	s_waitcnt lgkmcnt(0)
	v_add_f32_e32 v170, v170, v163
	ds_bpermute_b32 v163, v203, v170
	s_and_saveexec_b64 s[22:23], s[38:39]
	s_waitcnt lgkmcnt(0)
	v_add_f32_e32 v170, v170, v163
	v_mul_f32_e32 v170, 0x4b800000, v170
	v_trunc_f32_e32 v170, v170
	v_mul_f32_e32 v163, 0x2f800000, v170
	v_floor_f32_e32 v163, v163
	v_fmac_f32_e32 v170, 0xcf800000, v163
	v_cvt_u32_f32_e32 v172, v170
	v_cvt_u32_f32_e32 v173, v163
	s_mov_b32 s100, 0x180
	v_lshl_add_u64 v[184:185], v[200:201], 0, s[100:101]
	global_atomic_add_x2 v[184:185], v[172:173], off
	s_or_b64 exec, exec, s[22:23]
	s_mov_b32 s100, 0x120000
	v_lshl_add_u64 v[204:205], v[194:195], 0, s[100:101]
	global_load_dwordx4 v[230:233], v[204:205], off offset:512
	global_load_dwordx4 v[234:237], v[204:205], off offset:528
	s_waitcnt vmcnt(6)
	v_pk_add_f32 v[60:61], v[60:61], v[206:207]
	v_pk_add_f32 v[62:63], v[62:63], v[208:209]
	v_pk_add_f32 v[56:57], v[56:57], v[210:211]
	v_pk_add_f32 v[58:59], v[58:59], v[212:213]
	s_mov_b32 s100, 0x100000
	v_lshl_add_u64 v[182:183], v[196:197], 0, s[100:101]
	global_store_dwordx4 v[182:183], v[60:63], off
	global_store_dwordx4 v[182:183], v[56:59], off offset:16
	v_cvt_pk_bf16_f32 v186, v60, v61
	v_cvt_pk_bf16_f32 v187, v62, v63
	v_cvt_pk_bf16_f32 v188, v56, v57
	v_cvt_pk_bf16_f32 v189, v58, v59
	s_mov_b32 s100, 0x80000
	v_lshl_add_u64 v[184:185], v[198:199], 0, s[100:101]
	global_store_dwordx4 v[184:185], v[186:189], off
	v_mul_f32_e32 v170, v61, v61
	v_fmac_f32_e32 v170, v60, v60
	v_fmac_f32_e32 v170, v62, v62
	v_fmac_f32_e32 v170, v63, v63
	v_fmac_f32_e32 v170, v56, v56
	v_fmac_f32_e32 v170, v57, v57
	v_fmac_f32_e32 v170, v58, v58
	v_fmac_f32_e32 v170, v59, v59
	s_mov_b32 s100, 0x140000
	v_lshl_add_u64 v[204:205], v[194:195], 0, s[100:101]
	global_load_dwordx4 v[206:209], v[204:205], off
	global_load_dwordx4 v[210:213], v[204:205], off offset:16
	s_waitcnt vmcnt(6)
	v_pk_add_f32 v[52:53], v[52:53], v[214:215]
	v_pk_add_f32 v[54:55], v[54:55], v[216:217]
	v_pk_add_f32 v[48:49], v[48:49], v[218:219]
	v_pk_add_f32 v[50:51], v[50:51], v[220:221]
	s_mov_b32 s100, 0x100000
	v_lshl_add_u64 v[182:183], v[196:197], 0, s[100:101]
	global_store_dwordx4 v[182:183], v[52:55], off offset:512
	global_store_dwordx4 v[182:183], v[48:51], off offset:528
	v_cvt_pk_bf16_f32 v186, v52, v53
	v_cvt_pk_bf16_f32 v187, v54, v55
	v_cvt_pk_bf16_f32 v188, v48, v49
	v_cvt_pk_bf16_f32 v189, v50, v51
	s_mov_b32 s100, 0x80000
	v_lshl_add_u64 v[184:185], v[198:199], 0, s[100:101]
	global_store_dwordx4 v[184:185], v[186:189], off offset:256
	v_mul_f32_e32 v171, v53, v53
	v_fmac_f32_e32 v171, v52, v52
	v_fmac_f32_e32 v171, v54, v54
	v_fmac_f32_e32 v171, v55, v55
	v_fmac_f32_e32 v171, v48, v48
	v_fmac_f32_e32 v171, v49, v49
	v_fmac_f32_e32 v171, v50, v50
	v_fmac_f32_e32 v171, v51, v51
	v_add_f32_e32 v170, v170, v171
	ds_bpermute_b32 v163, v202, v170
	s_waitcnt lgkmcnt(0)
	v_add_f32_e32 v170, v170, v163
	ds_bpermute_b32 v163, v203, v170
	s_and_saveexec_b64 s[22:23], s[38:39]
	s_waitcnt lgkmcnt(0)
	v_add_f32_e32 v170, v170, v163
	v_mul_f32_e32 v170, 0x4b800000, v170
	v_trunc_f32_e32 v170, v170
	v_mul_f32_e32 v163, 0x2f800000, v170
	v_floor_f32_e32 v163, v163
	v_fmac_f32_e32 v170, 0xcf800000, v163
	v_cvt_u32_f32_e32 v172, v170
	v_cvt_u32_f32_e32 v173, v163
	s_mov_b32 s100, 0x400
	v_lshl_add_u64 v[184:185], v[200:201], 0, s[100:101]
	global_atomic_add_x2 v[184:185], v[172:173], off
	s_or_b64 exec, exec, s[22:23]
	s_mov_b32 s100, 0x140000
	v_lshl_add_u64 v[204:205], v[194:195], 0, s[100:101]
	global_load_dwordx4 v[214:217], v[204:205], off offset:512
	global_load_dwordx4 v[218:221], v[204:205], off offset:528
	s_waitcnt vmcnt(6)
	v_pk_add_f32 v[44:45], v[44:45], v[222:223]
	v_pk_add_f32 v[46:47], v[46:47], v[224:225]
	v_pk_add_f32 v[40:41], v[40:41], v[226:227]
	v_pk_add_f32 v[42:43], v[42:43], v[228:229]
	s_mov_b32 s100, 0x120000
	v_lshl_add_u64 v[182:183], v[196:197], 0, s[100:101]
	global_store_dwordx4 v[182:183], v[44:47], off
	global_store_dwordx4 v[182:183], v[40:43], off offset:16
	v_cvt_pk_bf16_f32 v186, v44, v45
	v_cvt_pk_bf16_f32 v187, v46, v47
	v_cvt_pk_bf16_f32 v188, v40, v41
	v_cvt_pk_bf16_f32 v189, v42, v43
	s_mov_b32 s100, 0x90000
	v_lshl_add_u64 v[184:185], v[198:199], 0, s[100:101]
	global_store_dwordx4 v[184:185], v[186:189], off
	v_mul_f32_e32 v170, v45, v45
	v_fmac_f32_e32 v170, v44, v44
	v_fmac_f32_e32 v170, v46, v46
	v_fmac_f32_e32 v170, v47, v47
	v_fmac_f32_e32 v170, v40, v40
	v_fmac_f32_e32 v170, v41, v41
	v_fmac_f32_e32 v170, v42, v42
	v_fmac_f32_e32 v170, v43, v43
	s_mov_b32 s100, 0x160000
	v_lshl_add_u64 v[204:205], v[194:195], 0, s[100:101]
	global_load_dwordx4 v[222:225], v[204:205], off
	global_load_dwordx4 v[226:229], v[204:205], off offset:16
	s_waitcnt vmcnt(6)
; __device__ __forceinline__ unsigned pk2(float lo, float hi) { const f32v2_t v = {lo, hi}; const bf16v2_t b = __builtin_convertvector(v, bf16v2_t); return __builtin_bit_cast(unsigned, b); }
; #define ST_OUT2(p, v) __builtin_nontemporal_store((v), (p))
; #define PG8_BAR __builtin_amdgcn_s_barrier()
; template <class Epi, class Sched>
; __device__ __forceinline__ void gemm_phase(LAS unsigned char* lds, const Gemm g, const Sched& S, const Epi& E) {
;     ...
;         if (!has_next) break;
; #pragma unroll
;         for (int a = 0; a < 2; ++a)
; #pragma unroll
;             for (int b = 0; b < 2; ++b)
; #pragma unroll
;                 for (int m = 0; m < 4; ++m)
; #pragma unroll
;                     for (int n = 0; n < 2; ++n) acc[a][b][m][n] = (f32x4){0.f, 0.f, 0.f, 0.f};
;         cur = nxt; cA = nA; cB = nB; ++ui;
;         if (Sched::SEGMENTED) nt = S.nt(cur);
;     ...
;         if (wr == 1) PG8_BAR;
;     __device__ __forceinline__ void operator()(AccRef acc, const Unit& u, int wr, int wc, int fr, int fq) const {
;     ...
;                 const int row = row0 + ai * HALF + m * 16;
;                 float ss = 0.f;
; #pragma unroll
;                 for (int bj = 0; bj < 2; ++bj) {
;                     const size_t off = (size_t)row * DM + col0 + bj * HALF;
;                     f32x4 x0 = *(const f32x4*)(xin + off), x1 = *(const f32x4*)(xin + off + 4);
;                     x0 = x0 + acc[ai][bj][m][0] * scale; x1 = x1 + acc[ai][bj][m][1] * scale;
;                     ST_OUT2((f32x4*)(xout + off), x0); ST_OUT2((f32x4*)(xout + off + 4), x1);
;                     u32x4 o; o.x = pk2(x0[0], x0[1]); o.y = pk2(x0[2], x0[3]); o.z = pk2(x1[0], x1[1]); o.w = pk2(x1[2], x1[3]);
;                     if (wxb) ST_OUT2((u32x4*)(XB + off), o);
;                     ss += x0[0] * x0[0] + x0[1] * x0[1] + x0[2] * x0[2] + x0[3] * x0[3] + x1[0] * x1[0] + x1[1] * x1[1] + x1[2] * x1[2] + x1[3] * x1[3];
;                 }
;                 ss += __shfl_xor(ss, 16); ss += __shfl_xor(ss, 32);
;                 if (fq == 0) atomicAdd(rssn + row, (unsigned long long)(ss * 16777216.f));
;             }
	v_pk_add_f32 v[36:37], v[36:37], v[230:231]
	v_pk_add_f32 v[38:39], v[38:39], v[232:233]
	v_pk_add_f32 v[32:33], v[32:33], v[234:235]
	v_pk_add_f32 v[34:35], v[34:35], v[236:237]
	s_mov_b32 s100, 0x120000
	v_lshl_add_u64 v[182:183], v[196:197], 0, s[100:101]
	global_store_dwordx4 v[182:183], v[36:39], off offset:512
	global_store_dwordx4 v[182:183], v[32:35], off offset:528
	v_cvt_pk_bf16_f32 v186, v36, v37
	v_cvt_pk_bf16_f32 v187, v38, v39
	v_cvt_pk_bf16_f32 v188, v32, v33
	v_cvt_pk_bf16_f32 v189, v34, v35
	s_mov_b32 s100, 0x90000
	v_lshl_add_u64 v[184:185], v[198:199], 0, s[100:101]
	global_store_dwordx4 v[184:185], v[186:189], off offset:256
	v_mul_f32_e32 v171, v37, v37
	v_fmac_f32_e32 v171, v36, v36
	v_fmac_f32_e32 v171, v38, v38
	v_fmac_f32_e32 v171, v39, v39
	v_fmac_f32_e32 v171, v32, v32
	v_fmac_f32_e32 v171, v33, v33
	v_fmac_f32_e32 v171, v34, v34
	v_fmac_f32_e32 v171, v35, v35
	v_add_f32_e32 v170, v170, v171
	ds_bpermute_b32 v163, v202, v170
	s_waitcnt lgkmcnt(0)
	v_add_f32_e32 v170, v170, v163
	ds_bpermute_b32 v163, v203, v170
	s_and_saveexec_b64 s[22:23], s[38:39]
	s_waitcnt lgkmcnt(0)
	v_add_f32_e32 v170, v170, v163
	v_mul_f32_e32 v170, 0x4b800000, v170
	v_trunc_f32_e32 v170, v170
	v_mul_f32_e32 v163, 0x2f800000, v170
	v_floor_f32_e32 v163, v163
	v_fmac_f32_e32 v170, 0xcf800000, v163
	v_cvt_u32_f32_e32 v172, v170
	v_cvt_u32_f32_e32 v173, v163
	s_mov_b32 s100, 0x480
	v_lshl_add_u64 v[184:185], v[200:201], 0, s[100:101]
	global_atomic_add_x2 v[184:185], v[172:173], off
	s_or_b64 exec, exec, s[22:23]
	s_mov_b32 s100, 0x160000
	v_lshl_add_u64 v[204:205], v[194:195], 0, s[100:101]
	global_load_dwordx4 v[230:233], v[204:205], off offset:512
	global_load_dwordx4 v[234:237], v[204:205], off offset:528
	s_waitcnt vmcnt(6)
	v_pk_add_f32 v[28:29], v[28:29], v[206:207]
	v_pk_add_f32 v[30:31], v[30:31], v[208:209]
	v_pk_add_f32 v[24:25], v[24:25], v[210:211]
	v_pk_add_f32 v[26:27], v[26:27], v[212:213]
	s_mov_b32 s100, 0x140000
	v_lshl_add_u64 v[182:183], v[196:197], 0, s[100:101]
	global_store_dwordx4 v[182:183], v[28:31], off
	global_store_dwordx4 v[182:183], v[24:27], off offset:16
	v_cvt_pk_bf16_f32 v186, v28, v29
	v_cvt_pk_bf16_f32 v187, v30, v31
	v_cvt_pk_bf16_f32 v188, v24, v25
	v_cvt_pk_bf16_f32 v189, v26, v27
	s_mov_b32 s100, 0xa0000
	v_lshl_add_u64 v[184:185], v[198:199], 0, s[100:101]
	global_store_dwordx4 v[184:185], v[186:189], off
	v_mul_f32_e32 v170, v29, v29
	v_fmac_f32_e32 v170, v28, v28
	v_fmac_f32_e32 v170, v30, v30
	v_fmac_f32_e32 v170, v31, v31
	v_fmac_f32_e32 v170, v24, v24
	v_fmac_f32_e32 v170, v25, v25
	v_fmac_f32_e32 v170, v26, v26
	v_fmac_f32_e32 v170, v27, v27
	s_waitcnt vmcnt(4)
	v_pk_add_f32 v[20:21], v[20:21], v[214:215]
	v_pk_add_f32 v[22:23], v[22:23], v[216:217]
	v_pk_add_f32 v[16:17], v[16:17], v[218:219]
	v_pk_add_f32 v[18:19], v[18:19], v[220:221]
	s_mov_b32 s100, 0x140000
	v_lshl_add_u64 v[182:183], v[196:197], 0, s[100:101]
	global_store_dwordx4 v[182:183], v[20:23], off offset:512
	global_store_dwordx4 v[182:183], v[16:19], off offset:528
	v_cvt_pk_bf16_f32 v186, v20, v21
	v_cvt_pk_bf16_f32 v187, v22, v23
	v_cvt_pk_bf16_f32 v188, v16, v17
	v_cvt_pk_bf16_f32 v189, v18, v19
	s_mov_b32 s100, 0xa0000
	v_lshl_add_u64 v[184:185], v[198:199], 0, s[100:101]
	global_store_dwordx4 v[184:185], v[186:189], off offset:256
	v_mul_f32_e32 v171, v21, v21
	v_fmac_f32_e32 v171, v20, v20
	v_fmac_f32_e32 v171, v22, v22
	v_fmac_f32_e32 v171, v23, v23
	v_fmac_f32_e32 v171, v16, v16
	v_fmac_f32_e32 v171, v17, v17
	v_fmac_f32_e32 v171, v18, v18
	v_fmac_f32_e32 v171, v19, v19
	v_add_f32_e32 v170, v170, v171
	ds_bpermute_b32 v163, v202, v170
	s_waitcnt lgkmcnt(0)
	v_add_f32_e32 v170, v170, v163
	ds_bpermute_b32 v163, v203, v170
	s_and_saveexec_b64 s[22:23], s[38:39]
	s_waitcnt lgkmcnt(0)
	v_add_f32_e32 v170, v170, v163
	v_mul_f32_e32 v170, 0x4b800000, v170
	v_trunc_f32_e32 v170, v170
	v_mul_f32_e32 v163, 0x2f800000, v170
	v_floor_f32_e32 v163, v163
	v_fmac_f32_e32 v170, 0xcf800000, v163
	v_cvt_u32_f32_e32 v172, v170
	v_cvt_u32_f32_e32 v173, v163
	s_mov_b32 s100, 0x500
	v_lshl_add_u64 v[184:185], v[200:201], 0, s[100:101]
	global_atomic_add_x2 v[184:185], v[172:173], off
	s_or_b64 exec, exec, s[22:23]
	s_waitcnt vmcnt(2)
	v_pk_add_f32 v[12:13], v[12:13], v[222:223]
	v_pk_add_f32 v[14:15], v[14:15], v[224:225]
	v_pk_add_f32 v[8:9], v[8:9], v[226:227]
	v_pk_add_f32 v[10:11], v[10:11], v[228:229]
	s_mov_b32 s100, 0x160000
	v_lshl_add_u64 v[182:183], v[196:197], 0, s[100:101]
	global_store_dwordx4 v[182:183], v[12:15], off
	global_store_dwordx4 v[182:183], v[8:11], off offset:16
	v_cvt_pk_bf16_f32 v186, v12, v13
	v_cvt_pk_bf16_f32 v187, v14, v15
	v_cvt_pk_bf16_f32 v188, v8, v9
	v_cvt_pk_bf16_f32 v189, v10, v11
	s_mov_b32 s100, 0xb0000
	v_lshl_add_u64 v[184:185], v[198:199], 0, s[100:101]
	global_store_dwordx4 v[184:185], v[186:189], off
	v_mul_f32_e32 v170, v13, v13
	v_fmac_f32_e32 v170, v12, v12
	v_fmac_f32_e32 v170, v14, v14
	v_fmac_f32_e32 v170, v15, v15
	v_fmac_f32_e32 v170, v8, v8
	v_fmac_f32_e32 v170, v9, v9
	v_fmac_f32_e32 v170, v10, v10
	v_fmac_f32_e32 v170, v11, v11
	s_waitcnt vmcnt(0)
	v_pk_add_f32 v[4:5], v[4:5], v[230:231]
	v_pk_add_f32 v[6:7], v[6:7], v[232:233]
	v_pk_add_f32 v[0:1], v[0:1], v[234:235]
	v_pk_add_f32 v[2:3], v[2:3], v[236:237]
	s_mov_b32 s100, 0x160000
	v_lshl_add_u64 v[182:183], v[196:197], 0, s[100:101]
	global_store_dwordx4 v[182:183], v[4:7], off offset:512
	global_store_dwordx4 v[182:183], v[0:3], off offset:528
	v_cvt_pk_bf16_f32 v186, v4, v5
	v_cvt_pk_bf16_f32 v187, v6, v7
	v_cvt_pk_bf16_f32 v188, v0, v1
	v_cvt_pk_bf16_f32 v189, v2, v3
	s_mov_b32 s100, 0xb0000
	v_lshl_add_u64 v[184:185], v[198:199], 0, s[100:101]
	global_store_dwordx4 v[184:185], v[186:189], off offset:256
	v_mul_f32_e32 v171, v5, v5
	v_fmac_f32_e32 v171, v4, v4
	v_fmac_f32_e32 v171, v6, v6
	v_fmac_f32_e32 v171, v7, v7
	v_fmac_f32_e32 v171, v0, v0
	v_fmac_f32_e32 v171, v1, v1
	v_fmac_f32_e32 v171, v2, v2
	v_fmac_f32_e32 v171, v3, v3
	v_add_f32_e32 v170, v170, v171
	ds_bpermute_b32 v163, v202, v170
	s_waitcnt lgkmcnt(0)
	v_add_f32_e32 v170, v170, v163
	ds_bpermute_b32 v163, v203, v170
	s_and_saveexec_b64 s[22:23], s[38:39]
	s_waitcnt lgkmcnt(0)
	v_add_f32_e32 v170, v170, v163
	v_mul_f32_e32 v170, 0x4b800000, v170
	v_trunc_f32_e32 v170, v170
	v_mul_f32_e32 v163, 0x2f800000, v170
	v_floor_f32_e32 v163, v163
	v_fmac_f32_e32 v170, 0xcf800000, v163
	v_cvt_u32_f32_e32 v172, v170
	v_cvt_u32_f32_e32 v173, v163
	s_mov_b32 s100, 0x580
	v_lshl_add_u64 v[184:185], v[200:201], 0, s[100:101]
	global_atomic_add_x2 v[184:185], v[172:173], off
	s_or_b64 exec, exec, s[22:23]
	s_movk_i32 s92, 0x37ff
	s_mov_b64 s[16:17], 0x58000
	s_andn2_b64 vcc, exec, s[40:41]
	s_mov_b64 s[22:23], -1
	s_cbranch_vccnz .LBB0_90
	s_andn2_b64 vcc, exec, s[0:1]
	s_cbranch_vccnz .LBB0_89
	s_barrier
	s_branch .LBB0_89

; __device__ __forceinline__ unsigned pk2(float lo, float hi) { const f32v2_t v = {lo, hi}; const bf16v2_t b = __builtin_convertvector(v, bf16v2_t); return __builtin_bit_cast(unsigned, b); }
; #define ST_OUT2(p, v) __builtin_nontemporal_store((v), (p))
;     __device__ __forceinline__ void operator()(AccRef acc, const Unit& u, int wr, int wc, int fr, int fq) const {
;         const int row0 = u.pm * BM + wr * 64 + fr, col0 = u.pn * BM + wc * 32 + 8 * fq;
; #pragma unroll
;         for (int ai = 0; ai < 2; ++ai)
; #pragma unroll
;             for (int m = 0; m < 4; ++m) {
;                 const int row = row0 + ai * HALF + m * 16;
;                 float ss = 0.f;
; #pragma unroll
;                 for (int bj = 0; bj < 2; ++bj) {
;                     const size_t off = (size_t)row * DM + col0 + bj * HALF;
;                     f32x4 x0 = *(const f32x4*)(xin + off), x1 = *(const f32x4*)(xin + off + 4);
;                     x0 = x0 + acc[ai][bj][m][0] * scale; x1 = x1 + acc[ai][bj][m][1] * scale;
;                     ST_OUT2((f32x4*)(xout + off), x0); ST_OUT2((f32x4*)(xout + off + 4), x1);
;                     u32x4 o; o.x = pk2(x0[0], x0[1]); o.y = pk2(x0[2], x0[3]); o.z = pk2(x1[0], x1[1]); o.w = pk2(x1[2], x1[3]);
;                     if (wxb) ST_OUT2((u32x4*)(XB + off), o);
;                     ss += x0[0] * x0[0] + x0[1] * x0[1] + x0[2] * x0[2] + x0[3] * x0[3] + x1[0] * x1[0] + x1[1] * x1[1] + x1[2] * x1[2] + x1[3] * x1[3];
;                 }
;                 ss += __shfl_xor(ss, 16); ss += __shfl_xor(ss, 32);
;                 if (fq == 0) atomicAdd(rssn + row, (unsigned long long)(ss * 16777216.f));
;             }
.LBB0_682:
	v_lshl_add_u32 v156, s61, 8, v166
	v_lshl_or_b32 v160, s60, 8, v168
	v_ashrrev_i32_e32 v157, 31, v156
	v_ashrrev_i32_e32 v161, 31, v160
	v_lshlrev_b64 v[158:159], 11, v[156:157]
	v_lshl_add_u64 v[158:159], v[158:159], 0, v[160:161]
	v_lshl_add_u64 v[194:195], v[158:159], 2, s[44:45]
	v_lshl_add_u64 v[196:197], v[158:159], 2, s[80:81]
	v_lshl_add_u64 v[198:199], v[158:159], 1, s[90:91]
	v_lshl_add_u64 v[200:201], v[156:157], 3, s[46:47]
	v_and_b32_e32 v204, 64, v177
	v_add_u32_e32 v204, 64, v204
	v_xor_b32_e32 v202, 16, v177
	v_xor_b32_e32 v203, 32, v177
	v_cmp_lt_i32_e32 vcc, v202, v204
	s_nop 1
	v_cndmask_b32_e32 v202, v177, v202, vcc
	v_cmp_lt_i32_e32 vcc, v203, v204
	s_nop 1
	v_cndmask_b32_e32 v203, v177, v203, vcc
	v_lshlrev_b32_e32 v202, 2, v202
	v_lshlrev_b32_e32 v203, 2, v203
	s_mov_b32 s101, 0
	s_and_b64 vcc, exec, s[48:49]
	s_cbranch_vccz .Lrs2_nowxb
	s_mov_b32 s100, 0x0
	v_lshl_add_u64 v[204:205], v[194:195], 0, s[100:101]
	global_load_dwordx4 v[206:209], v[204:205], off
	global_load_dwordx4 v[210:213], v[204:205], off offset:16
	s_mov_b32 s100, 0x0
	v_lshl_add_u64 v[204:205], v[194:195], 0, s[100:101]
	global_load_dwordx4 v[214:217], v[204:205], off offset:512
	global_load_dwordx4 v[218:221], v[204:205], off offset:528
	s_mov_b32 s100, 0x20000
	v_lshl_add_u64 v[204:205], v[194:195], 0, s[100:101]
	global_load_dwordx4 v[222:225], v[204:205], off
	global_load_dwordx4 v[226:229], v[204:205], off offset:16
	s_mov_b32 s100, 0x20000
	v_lshl_add_u64 v[204:205], v[194:195], 0, s[100:101]
	global_load_dwordx4 v[230:233], v[204:205], off offset:512
	global_load_dwordx4 v[234:237], v[204:205], off offset:528
	s_waitcnt vmcnt(6)
	v_pk_fma_f32 v[124:125], v[124:125], 0.5, v[206:207] op_sel_hi:[1,0,1]
	v_pk_fma_f32 v[126:127], v[126:127], 0.5, v[208:209] op_sel_hi:[1,0,1]
	v_pk_fma_f32 v[120:121], v[120:121], 0.5, v[210:211] op_sel_hi:[1,0,1]
	v_pk_fma_f32 v[122:123], v[122:123], 0.5, v[212:213] op_sel_hi:[1,0,1]
	s_mov_b32 s100, 0x0
	v_lshl_add_u64 v[182:183], v[196:197], 0, s[100:101]
	global_store_dwordx4 v[182:183], v[124:127], off
	global_store_dwordx4 v[182:183], v[120:123], off offset:16
	v_cvt_pk_bf16_f32 v186, v124, v125
	v_cvt_pk_bf16_f32 v187, v126, v127
	v_cvt_pk_bf16_f32 v188, v120, v121
	v_cvt_pk_bf16_f32 v189, v122, v123
	s_mov_b32 s100, 0x0
	v_lshl_add_u64 v[184:185], v[198:199], 0, s[100:101]
	global_store_dwordx4 v[184:185], v[186:189], off
	v_mul_f32_e32 v170, v125, v125
	v_fmac_f32_e32 v170, v124, v124
	v_fmac_f32_e32 v170, v126, v126
	v_fmac_f32_e32 v170, v127, v127
	v_fmac_f32_e32 v170, v120, v120
	v_fmac_f32_e32 v170, v121, v121
	v_fmac_f32_e32 v170, v122, v122
	v_fmac_f32_e32 v170, v123, v123
	s_mov_b32 s100, 0x40000
	v_lshl_add_u64 v[204:205], v[194:195], 0, s[100:101]
	global_load_dwordx4 v[206:209], v[204:205], off
	global_load_dwordx4 v[210:213], v[204:205], off offset:16
	s_waitcnt vmcnt(6)
	v_pk_fma_f32 v[116:117], v[116:117], 0.5, v[214:215] op_sel_hi:[1,0,1]
	v_pk_fma_f32 v[118:119], v[118:119], 0.5, v[216:217] op_sel_hi:[1,0,1]
	v_pk_fma_f32 v[112:113], v[112:113], 0.5, v[218:219] op_sel_hi:[1,0,1]
	v_pk_fma_f32 v[114:115], v[114:115], 0.5, v[220:221] op_sel_hi:[1,0,1]
	s_mov_b32 s100, 0x0
	v_lshl_add_u64 v[182:183], v[196:197], 0, s[100:101]
	global_store_dwordx4 v[182:183], v[116:119], off offset:512
	global_store_dwordx4 v[182:183], v[112:115], off offset:528
	v_cvt_pk_bf16_f32 v186, v116, v117
	v_cvt_pk_bf16_f32 v187, v118, v119
	v_cvt_pk_bf16_f32 v188, v112, v113
	v_cvt_pk_bf16_f32 v189, v114, v115
	s_mov_b32 s100, 0x0
	v_lshl_add_u64 v[184:185], v[198:199], 0, s[100:101]
	global_store_dwordx4 v[184:185], v[186:189], off offset:256
	v_mul_f32_e32 v171, v117, v117
	v_fmac_f32_e32 v171, v116, v116
	v_fmac_f32_e32 v171, v118, v118
	v_fmac_f32_e32 v171, v119, v119
	v_fmac_f32_e32 v171, v112, v112
	v_fmac_f32_e32 v171, v113, v113
	v_fmac_f32_e32 v171, v114, v114
	v_fmac_f32_e32 v171, v115, v115
	v_add_f32_e32 v170, v170, v171
	ds_bpermute_b32 v163, v202, v170
	s_waitcnt lgkmcnt(0)
	v_add_f32_e32 v170, v170, v163
	ds_bpermute_b32 v163, v203, v170
	s_and_saveexec_b64 s[54:55], s[38:39]
	s_waitcnt lgkmcnt(0)
	v_add_f32_e32 v170, v170, v163
	v_mul_f32_e32 v170, 0x4b800000, v170
	v_trunc_f32_e32 v170, v170
	v_mul_f32_e32 v163, 0x2f800000, v170
	v_floor_f32_e32 v163, v163
	v_fmac_f32_e32 v170, 0xcf800000, v163
	v_cvt_u32_f32_e32 v172, v170
	v_cvt_u32_f32_e32 v173, v163
	s_mov_b32 s100, 0x0
	v_lshl_add_u64 v[184:185], v[200:201], 0, s[100:101]
	global_atomic_add_x2 v[184:185], v[172:173], off
	s_or_b64 exec, exec, s[54:55]
	s_mov_b32 s100, 0x40000
	v_lshl_add_u64 v[204:205], v[194:195], 0, s[100:101]
	global_load_dwordx4 v[214:217], v[204:205], off offset:512
	global_load_dwordx4 v[218:221], v[204:205], off offset:528
	s_waitcnt vmcnt(6)
	v_pk_fma_f32 v[108:109], v[108:109], 0.5, v[222:223] op_sel_hi:[1,0,1]
	v_pk_fma_f32 v[110:111], v[110:111], 0.5, v[224:225] op_sel_hi:[1,0,1]
	v_pk_fma_f32 v[104:105], v[104:105], 0.5, v[226:227] op_sel_hi:[1,0,1]
	v_pk_fma_f32 v[106:107], v[106:107], 0.5, v[228:229] op_sel_hi:[1,0,1]
	s_mov_b32 s100, 0x20000
	v_lshl_add_u64 v[182:183], v[196:197], 0, s[100:101]
	global_store_dwordx4 v[182:183], v[108:111], off
	global_store_dwordx4 v[182:183], v[104:107], off offset:16
	v_cvt_pk_bf16_f32 v186, v108, v109
	v_cvt_pk_bf16_f32 v187, v110, v111
	v_cvt_pk_bf16_f32 v188, v104, v105
	v_cvt_pk_bf16_f32 v189, v106, v107
	s_mov_b32 s100, 0x10000
	v_lshl_add_u64 v[184:185], v[198:199], 0, s[100:101]
	global_store_dwordx4 v[184:185], v[186:189], off
	v_mul_f32_e32 v170, v109, v109
	v_fmac_f32_e32 v170, v108, v108
	v_fmac_f32_e32 v170, v110, v110
	v_fmac_f32_e32 v170, v111, v111
	v_fmac_f32_e32 v170, v104, v104
	v_fmac_f32_e32 v170, v105, v105
	v_fmac_f32_e32 v170, v106, v106
	v_fmac_f32_e32 v170, v107, v107
	s_mov_b32 s100, 0x60000
	v_lshl_add_u64 v[204:205], v[194:195], 0, s[100:101]
	global_load_dwordx4 v[222:225], v[204:205], off
	global_load_dwordx4 v[226:229], v[204:205], off offset:16
	s_waitcnt vmcnt(6)
; __device__ __forceinline__ unsigned pk2(float lo, float hi) { const f32v2_t v = {lo, hi}; const bf16v2_t b = __builtin_convertvector(v, bf16v2_t); return __builtin_bit_cast(unsigned, b); }
; #define ST_OUT2(p, v) __builtin_nontemporal_store((v), (p))
;     __device__ __forceinline__ void operator()(AccRef acc, const Unit& u, int wr, int wc, int fr, int fq) const {
;     ...
;                 const int row = row0 + ai * HALF + m * 16;
;                 float ss = 0.f;
; #pragma unroll
;                 for (int bj = 0; bj < 2; ++bj) {
;                     const size_t off = (size_t)row * DM + col0 + bj * HALF;
;                     f32x4 x0 = *(const f32x4*)(xin + off), x1 = *(const f32x4*)(xin + off + 4);
;                     x0 = x0 + acc[ai][bj][m][0] * scale; x1 = x1 + acc[ai][bj][m][1] * scale;
;                     ST_OUT2((f32x4*)(xout + off), x0); ST_OUT2((f32x4*)(xout + off + 4), x1);
;                     u32x4 o; o.x = pk2(x0[0], x0[1]); o.y = pk2(x0[2], x0[3]); o.z = pk2(x1[0], x1[1]); o.w = pk2(x1[2], x1[3]);
;                     if (wxb) ST_OUT2((u32x4*)(XB + off), o);
;                     ss += x0[0] * x0[0] + x0[1] * x0[1] + x0[2] * x0[2] + x0[3] * x0[3] + x1[0] * x1[0] + x1[1] * x1[1] + x1[2] * x1[2] + x1[3] * x1[3];
;                 }
;                 ss += __shfl_xor(ss, 16); ss += __shfl_xor(ss, 32);
;                 if (fq == 0) atomicAdd(rssn + row, (unsigned long long)(ss * 16777216.f));
;             }
	v_pk_fma_f32 v[100:101], v[100:101], 0.5, v[230:231] op_sel_hi:[1,0,1]
	v_pk_fma_f32 v[102:103], v[102:103], 0.5, v[232:233] op_sel_hi:[1,0,1]
	v_pk_fma_f32 v[96:97], v[96:97], 0.5, v[234:235] op_sel_hi:[1,0,1]
	v_pk_fma_f32 v[98:99], v[98:99], 0.5, v[236:237] op_sel_hi:[1,0,1]
	s_mov_b32 s100, 0x20000
	v_lshl_add_u64 v[182:183], v[196:197], 0, s[100:101]
	global_store_dwordx4 v[182:183], v[100:103], off offset:512
	global_store_dwordx4 v[182:183], v[96:99], off offset:528
	v_cvt_pk_bf16_f32 v186, v100, v101
	v_cvt_pk_bf16_f32 v187, v102, v103
	v_cvt_pk_bf16_f32 v188, v96, v97
	v_cvt_pk_bf16_f32 v189, v98, v99
	s_mov_b32 s100, 0x10000
	v_lshl_add_u64 v[184:185], v[198:199], 0, s[100:101]
	global_store_dwordx4 v[184:185], v[186:189], off offset:256
	v_mul_f32_e32 v171, v101, v101
	v_fmac_f32_e32 v171, v100, v100
	v_fmac_f32_e32 v171, v102, v102
	v_fmac_f32_e32 v171, v103, v103
	v_fmac_f32_e32 v171, v96, v96
	v_fmac_f32_e32 v171, v97, v97
	v_fmac_f32_e32 v171, v98, v98
	v_fmac_f32_e32 v171, v99, v99
	v_add_f32_e32 v170, v170, v171
	ds_bpermute_b32 v163, v202, v170
	s_waitcnt lgkmcnt(0)
	v_add_f32_e32 v170, v170, v163
	ds_bpermute_b32 v163, v203, v170
	s_and_saveexec_b64 s[54:55], s[38:39]
	s_waitcnt lgkmcnt(0)
	v_add_f32_e32 v170, v170, v163
	v_mul_f32_e32 v170, 0x4b800000, v170
	v_trunc_f32_e32 v170, v170
	v_mul_f32_e32 v163, 0x2f800000, v170
	v_floor_f32_e32 v163, v163
	v_fmac_f32_e32 v170, 0xcf800000, v163
	v_cvt_u32_f32_e32 v172, v170
	v_cvt_u32_f32_e32 v173, v163
	s_mov_b32 s100, 0x80
	v_lshl_add_u64 v[184:185], v[200:201], 0, s[100:101]
	global_atomic_add_x2 v[184:185], v[172:173], off
	s_or_b64 exec, exec, s[54:55]
	s_mov_b32 s100, 0x60000
	v_lshl_add_u64 v[204:205], v[194:195], 0, s[100:101]
	global_load_dwordx4 v[230:233], v[204:205], off offset:512
	global_load_dwordx4 v[234:237], v[204:205], off offset:528
	s_waitcnt vmcnt(6)
	v_pk_fma_f32 v[92:93], v[92:93], 0.5, v[206:207] op_sel_hi:[1,0,1]
	v_pk_fma_f32 v[94:95], v[94:95], 0.5, v[208:209] op_sel_hi:[1,0,1]
	v_pk_fma_f32 v[88:89], v[88:89], 0.5, v[210:211] op_sel_hi:[1,0,1]
	v_pk_fma_f32 v[90:91], v[90:91], 0.5, v[212:213] op_sel_hi:[1,0,1]
	s_mov_b32 s100, 0x40000
	v_lshl_add_u64 v[182:183], v[196:197], 0, s[100:101]
	global_store_dwordx4 v[182:183], v[92:95], off
	global_store_dwordx4 v[182:183], v[88:91], off offset:16
	v_cvt_pk_bf16_f32 v186, v92, v93
	v_cvt_pk_bf16_f32 v187, v94, v95
	v_cvt_pk_bf16_f32 v188, v88, v89
	v_cvt_pk_bf16_f32 v189, v90, v91
	s_mov_b32 s100, 0x20000
	v_lshl_add_u64 v[184:185], v[198:199], 0, s[100:101]
	global_store_dwordx4 v[184:185], v[186:189], off
	v_mul_f32_e32 v170, v93, v93
	v_fmac_f32_e32 v170, v92, v92
	v_fmac_f32_e32 v170, v94, v94
	v_fmac_f32_e32 v170, v95, v95
	v_fmac_f32_e32 v170, v88, v88
	v_fmac_f32_e32 v170, v89, v89
	v_fmac_f32_e32 v170, v90, v90
	v_fmac_f32_e32 v170, v91, v91
	s_mov_b32 s100, 0x100000
	v_lshl_add_u64 v[204:205], v[194:195], 0, s[100:101]
	global_load_dwordx4 v[206:209], v[204:205], off
	global_load_dwordx4 v[210:213], v[204:205], off offset:16
	s_waitcnt vmcnt(6)
	v_pk_fma_f32 v[84:85], v[84:85], 0.5, v[214:215] op_sel_hi:[1,0,1]
	v_pk_fma_f32 v[86:87], v[86:87], 0.5, v[216:217] op_sel_hi:[1,0,1]
	v_pk_fma_f32 v[80:81], v[80:81], 0.5, v[218:219] op_sel_hi:[1,0,1]
	v_pk_fma_f32 v[82:83], v[82:83], 0.5, v[220:221] op_sel_hi:[1,0,1]
	s_mov_b32 s100, 0x40000
	v_lshl_add_u64 v[182:183], v[196:197], 0, s[100:101]
	global_store_dwordx4 v[182:183], v[84:87], off offset:512
	global_store_dwordx4 v[182:183], v[80:83], off offset:528
	v_cvt_pk_bf16_f32 v186, v84, v85
	v_cvt_pk_bf16_f32 v187, v86, v87
	v_cvt_pk_bf16_f32 v188, v80, v81
	v_cvt_pk_bf16_f32 v189, v82, v83
	s_mov_b32 s100, 0x20000
	v_lshl_add_u64 v[184:185], v[198:199], 0, s[100:101]
	global_store_dwordx4 v[184:185], v[186:189], off offset:256
	v_mul_f32_e32 v171, v85, v85
	v_fmac_f32_e32 v171, v84, v84
	v_fmac_f32_e32 v171, v86, v86
	v_fmac_f32_e32 v171, v87, v87
	v_fmac_f32_e32 v171, v80, v80
	v_fmac_f32_e32 v171, v81, v81
	v_fmac_f32_e32 v171, v82, v82
	v_fmac_f32_e32 v171, v83, v83
	v_add_f32_e32 v170, v170, v171
	ds_bpermute_b32 v163, v202, v170
	s_waitcnt lgkmcnt(0)
	v_add_f32_e32 v170, v170, v163
	ds_bpermute_b32 v163, v203, v170
	s_and_saveexec_b64 s[54:55], s[38:39]
	s_waitcnt lgkmcnt(0)
	v_add_f32_e32 v170, v170, v163
	v_mul_f32_e32 v170, 0x4b800000, v170
	v_trunc_f32_e32 v170, v170
	v_mul_f32_e32 v163, 0x2f800000, v170
	v_floor_f32_e32 v163, v163
	v_fmac_f32_e32 v170, 0xcf800000, v163
	v_cvt_u32_f32_e32 v172, v170
	v_cvt_u32_f32_e32 v173, v163
	s_mov_b32 s100, 0x100
	v_lshl_add_u64 v[184:185], v[200:201], 0, s[100:101]
	global_atomic_add_x2 v[184:185], v[172:173], off
	s_or_b64 exec, exec, s[54:55]
	s_mov_b32 s100, 0x100000
	v_lshl_add_u64 v[204:205], v[194:195], 0, s[100:101]
	global_load_dwordx4 v[214:217], v[204:205], off offset:512
	global_load_dwordx4 v[218:221], v[204:205], off offset:528
	s_waitcnt vmcnt(6)
	v_pk_fma_f32 v[76:77], v[76:77], 0.5, v[222:223] op_sel_hi:[1,0,1]
	v_pk_fma_f32 v[78:79], v[78:79], 0.5, v[224:225] op_sel_hi:[1,0,1]
	v_pk_fma_f32 v[72:73], v[72:73], 0.5, v[226:227] op_sel_hi:[1,0,1]
	v_pk_fma_f32 v[74:75], v[74:75], 0.5, v[228:229] op_sel_hi:[1,0,1]
	s_mov_b32 s100, 0x60000
	v_lshl_add_u64 v[182:183], v[196:197], 0, s[100:101]
	global_store_dwordx4 v[182:183], v[76:79], off
	global_store_dwordx4 v[182:183], v[72:75], off offset:16
	v_cvt_pk_bf16_f32 v186, v76, v77
	v_cvt_pk_bf16_f32 v187, v78, v79
	v_cvt_pk_bf16_f32 v188, v72, v73
	v_cvt_pk_bf16_f32 v189, v74, v75
	s_mov_b32 s100, 0x30000
	v_lshl_add_u64 v[184:185], v[198:199], 0, s[100:101]
	global_store_dwordx4 v[184:185], v[186:189], off
	v_mul_f32_e32 v170, v77, v77
	v_fmac_f32_e32 v170, v76, v76
	v_fmac_f32_e32 v170, v78, v78
	v_fmac_f32_e32 v170, v79, v79
	v_fmac_f32_e32 v170, v72, v72
	v_fmac_f32_e32 v170, v73, v73
	v_fmac_f32_e32 v170, v74, v74
	v_fmac_f32_e32 v170, v75, v75
	s_mov_b32 s100, 0x120000
	v_lshl_add_u64 v[204:205], v[194:195], 0, s[100:101]
	global_load_dwordx4 v[222:225], v[204:205], off
	global_load_dwordx4 v[226:229], v[204:205], off offset:16
	s_waitcnt vmcnt(6)
; __device__ __forceinline__ unsigned pk2(float lo, float hi) { const f32v2_t v = {lo, hi}; const bf16v2_t b = __builtin_convertvector(v, bf16v2_t); return __builtin_bit_cast(unsigned, b); }
; #define ST_OUT2(p, v) __builtin_nontemporal_store((v), (p))
;     __device__ __forceinline__ void operator()(AccRef acc, const Unit& u, int wr, int wc, int fr, int fq) const {
;     ...
;                 const int row = row0 + ai * HALF + m * 16;
;                 float ss = 0.f;
; #pragma unroll
;                 for (int bj = 0; bj < 2; ++bj) {
;                     const size_t off = (size_t)row * DM + col0 + bj * HALF;
;                     f32x4 x0 = *(const f32x4*)(xin + off), x1 = *(const f32x4*)(xin + off + 4);
;                     x0 = x0 + acc[ai][bj][m][0] * scale; x1 = x1 + acc[ai][bj][m][1] * scale;
;                     ST_OUT2((f32x4*)(xout + off), x0); ST_OUT2((f32x4*)(xout + off + 4), x1);
;                     u32x4 o; o.x = pk2(x0[0], x0[1]); o.y = pk2(x0[2], x0[3]); o.z = pk2(x1[0], x1[1]); o.w = pk2(x1[2], x1[3]);
;                     if (wxb) ST_OUT2((u32x4*)(XB + off), o);
;                     ss += x0[0] * x0[0] + x0[1] * x0[1] + x0[2] * x0[2] + x0[3] * x0[3] + x1[0] * x1[0] + x1[1] * x1[1] + x1[2] * x1[2] + x1[3] * x1[3];
;                 }
;                 ss += __shfl_xor(ss, 16); ss += __shfl_xor(ss, 32);
;                 if (fq == 0) atomicAdd(rssn + row, (unsigned long long)(ss * 16777216.f));
;             }
	v_pk_fma_f32 v[68:69], v[68:69], 0.5, v[230:231] op_sel_hi:[1,0,1]
	v_pk_fma_f32 v[70:71], v[70:71], 0.5, v[232:233] op_sel_hi:[1,0,1]
	v_pk_fma_f32 v[64:65], v[64:65], 0.5, v[234:235] op_sel_hi:[1,0,1]
	v_pk_fma_f32 v[66:67], v[66:67], 0.5, v[236:237] op_sel_hi:[1,0,1]
	s_mov_b32 s100, 0x60000
	v_lshl_add_u64 v[182:183], v[196:197], 0, s[100:101]
	global_store_dwordx4 v[182:183], v[68:71], off offset:512
	global_store_dwordx4 v[182:183], v[64:67], off offset:528
	v_cvt_pk_bf16_f32 v186, v68, v69
	v_cvt_pk_bf16_f32 v187, v70, v71
	v_cvt_pk_bf16_f32 v188, v64, v65
	v_cvt_pk_bf16_f32 v189, v66, v67
	s_mov_b32 s100, 0x30000
	v_lshl_add_u64 v[184:185], v[198:199], 0, s[100:101]
	global_store_dwordx4 v[184:185], v[186:189], off offset:256
	v_mul_f32_e32 v171, v69, v69
	v_fmac_f32_e32 v171, v68, v68
	v_fmac_f32_e32 v171, v70, v70
	v_fmac_f32_e32 v171, v71, v71
	v_fmac_f32_e32 v171, v64, v64
	v_fmac_f32_e32 v171, v65, v65
	v_fmac_f32_e32 v171, v66, v66
	v_fmac_f32_e32 v171, v67, v67
	v_add_f32_e32 v170, v170, v171
	ds_bpermute_b32 v163, v202, v170
	s_waitcnt lgkmcnt(0)
	v_add_f32_e32 v170, v170, v163
	ds_bpermute_b32 v163, v203, v170
	s_and_saveexec_b64 s[54:55], s[38:39]
	s_waitcnt lgkmcnt(0)
	v_add_f32_e32 v170, v170, v163
	v_mul_f32_e32 v170, 0x4b800000, v170
	v_trunc_f32_e32 v170, v170
	v_mul_f32_e32 v163, 0x2f800000, v170
	v_floor_f32_e32 v163, v163
	v_fmac_f32_e32 v170, 0xcf800000, v163
	v_cvt_u32_f32_e32 v172, v170
	v_cvt_u32_f32_e32 v173, v163
	s_mov_b32 s100, 0x180
	v_lshl_add_u64 v[184:185], v[200:201], 0, s[100:101]
	global_atomic_add_x2 v[184:185], v[172:173], off
	s_or_b64 exec, exec, s[54:55]
	s_mov_b32 s100, 0x120000
	v_lshl_add_u64 v[204:205], v[194:195], 0, s[100:101]
	global_load_dwordx4 v[230:233], v[204:205], off offset:512
	global_load_dwordx4 v[234:237], v[204:205], off offset:528
	s_waitcnt vmcnt(6)
	v_pk_fma_f32 v[60:61], v[60:61], 0.5, v[206:207] op_sel_hi:[1,0,1]
	v_pk_fma_f32 v[62:63], v[62:63], 0.5, v[208:209] op_sel_hi:[1,0,1]
	v_pk_fma_f32 v[56:57], v[56:57], 0.5, v[210:211] op_sel_hi:[1,0,1]
	v_pk_fma_f32 v[58:59], v[58:59], 0.5, v[212:213] op_sel_hi:[1,0,1]
	s_mov_b32 s100, 0x100000
	v_lshl_add_u64 v[182:183], v[196:197], 0, s[100:101]
	global_store_dwordx4 v[182:183], v[60:63], off
	global_store_dwordx4 v[182:183], v[56:59], off offset:16
	v_cvt_pk_bf16_f32 v186, v60, v61
	v_cvt_pk_bf16_f32 v187, v62, v63
	v_cvt_pk_bf16_f32 v188, v56, v57
	v_cvt_pk_bf16_f32 v189, v58, v59
	s_mov_b32 s100, 0x80000
	v_lshl_add_u64 v[184:185], v[198:199], 0, s[100:101]
	global_store_dwordx4 v[184:185], v[186:189], off
	v_mul_f32_e32 v170, v61, v61
	v_fmac_f32_e32 v170, v60, v60
	v_fmac_f32_e32 v170, v62, v62
	v_fmac_f32_e32 v170, v63, v63
	v_fmac_f32_e32 v170, v56, v56
	v_fmac_f32_e32 v170, v57, v57
	v_fmac_f32_e32 v170, v58, v58
	v_fmac_f32_e32 v170, v59, v59
	s_mov_b32 s100, 0x140000
	v_lshl_add_u64 v[204:205], v[194:195], 0, s[100:101]
	global_load_dwordx4 v[206:209], v[204:205], off
	global_load_dwordx4 v[210:213], v[204:205], off offset:16
	s_waitcnt vmcnt(6)
	v_pk_fma_f32 v[52:53], v[52:53], 0.5, v[214:215] op_sel_hi:[1,0,1]
	v_pk_fma_f32 v[54:55], v[54:55], 0.5, v[216:217] op_sel_hi:[1,0,1]
	v_pk_fma_f32 v[48:49], v[48:49], 0.5, v[218:219] op_sel_hi:[1,0,1]
	v_pk_fma_f32 v[50:51], v[50:51], 0.5, v[220:221] op_sel_hi:[1,0,1]
	s_mov_b32 s100, 0x100000
	v_lshl_add_u64 v[182:183], v[196:197], 0, s[100:101]
	global_store_dwordx4 v[182:183], v[52:55], off offset:512
	global_store_dwordx4 v[182:183], v[48:51], off offset:528
	v_cvt_pk_bf16_f32 v186, v52, v53
	v_cvt_pk_bf16_f32 v187, v54, v55
	v_cvt_pk_bf16_f32 v188, v48, v49
	v_cvt_pk_bf16_f32 v189, v50, v51
	s_mov_b32 s100, 0x80000
	v_lshl_add_u64 v[184:185], v[198:199], 0, s[100:101]
	global_store_dwordx4 v[184:185], v[186:189], off offset:256
	v_mul_f32_e32 v171, v53, v53
	v_fmac_f32_e32 v171, v52, v52
	v_fmac_f32_e32 v171, v54, v54
	v_fmac_f32_e32 v171, v55, v55
	v_fmac_f32_e32 v171, v48, v48
	v_fmac_f32_e32 v171, v49, v49
	v_fmac_f32_e32 v171, v50, v50
	v_fmac_f32_e32 v171, v51, v51
	v_add_f32_e32 v170, v170, v171
	ds_bpermute_b32 v163, v202, v170
	s_waitcnt lgkmcnt(0)
	v_add_f32_e32 v170, v170, v163
	ds_bpermute_b32 v163, v203, v170
	s_and_saveexec_b64 s[54:55], s[38:39]
	s_waitcnt lgkmcnt(0)
	v_add_f32_e32 v170, v170, v163
	v_mul_f32_e32 v170, 0x4b800000, v170
	v_trunc_f32_e32 v170, v170
	v_mul_f32_e32 v163, 0x2f800000, v170
	v_floor_f32_e32 v163, v163
	v_fmac_f32_e32 v170, 0xcf800000, v163
	v_cvt_u32_f32_e32 v172, v170
	v_cvt_u32_f32_e32 v173, v163
	s_mov_b32 s100, 0x400
	v_lshl_add_u64 v[184:185], v[200:201], 0, s[100:101]
	global_atomic_add_x2 v[184:185], v[172:173], off
	s_or_b64 exec, exec, s[54:55]
	s_mov_b32 s100, 0x140000
	v_lshl_add_u64 v[204:205], v[194:195], 0, s[100:101]
	global_load_dwordx4 v[214:217], v[204:205], off offset:512
	global_load_dwordx4 v[218:221], v[204:205], off offset:528
	s_waitcnt vmcnt(6)
	v_pk_fma_f32 v[44:45], v[44:45], 0.5, v[222:223] op_sel_hi:[1,0,1]
	v_pk_fma_f32 v[46:47], v[46:47], 0.5, v[224:225] op_sel_hi:[1,0,1]
	v_pk_fma_f32 v[40:41], v[40:41], 0.5, v[226:227] op_sel_hi:[1,0,1]
	v_pk_fma_f32 v[42:43], v[42:43], 0.5, v[228:229] op_sel_hi:[1,0,1]
	s_mov_b32 s100, 0x120000
	v_lshl_add_u64 v[182:183], v[196:197], 0, s[100:101]
	global_store_dwordx4 v[182:183], v[44:47], off
	global_store_dwordx4 v[182:183], v[40:43], off offset:16
	v_cvt_pk_bf16_f32 v186, v44, v45
	v_cvt_pk_bf16_f32 v187, v46, v47
	v_cvt_pk_bf16_f32 v188, v40, v41
	v_cvt_pk_bf16_f32 v189, v42, v43
	s_mov_b32 s100, 0x90000
	v_lshl_add_u64 v[184:185], v[198:199], 0, s[100:101]
	global_store_dwordx4 v[184:185], v[186:189], off
	v_mul_f32_e32 v170, v45, v45
	v_fmac_f32_e32 v170, v44, v44
	v_fmac_f32_e32 v170, v46, v46
	v_fmac_f32_e32 v170, v47, v47
	v_fmac_f32_e32 v170, v40, v40
	v_fmac_f32_e32 v170, v41, v41
	v_fmac_f32_e32 v170, v42, v42
	v_fmac_f32_e32 v170, v43, v43
	s_mov_b32 s100, 0x160000
	v_lshl_add_u64 v[204:205], v[194:195], 0, s[100:101]
	global_load_dwordx4 v[222:225], v[204:205], off
	global_load_dwordx4 v[226:229], v[204:205], off offset:16
	s_waitcnt vmcnt(6)
; __device__ __forceinline__ unsigned pk2(float lo, float hi) { const f32v2_t v = {lo, hi}; const bf16v2_t b = __builtin_convertvector(v, bf16v2_t); return __builtin_bit_cast(unsigned, b); }
; #define ST_OUT2(p, v) __builtin_nontemporal_store((v), (p))
;     __device__ __forceinline__ void operator()(AccRef acc, const Unit& u, int wr, int wc, int fr, int fq) const {
;     ...
;                 const int row = row0 + ai * HALF + m * 16;
;                 float ss = 0.f;
; #pragma unroll
;                 for (int bj = 0; bj < 2; ++bj) {
;                     const size_t off = (size_t)row * DM + col0 + bj * HALF;
;                     f32x4 x0 = *(const f32x4*)(xin + off), x1 = *(const f32x4*)(xin + off + 4);
;                     x0 = x0 + acc[ai][bj][m][0] * scale; x1 = x1 + acc[ai][bj][m][1] * scale;
;                     ST_OUT2((f32x4*)(xout + off), x0); ST_OUT2((f32x4*)(xout + off + 4), x1);
;                     u32x4 o; o.x = pk2(x0[0], x0[1]); o.y = pk2(x0[2], x0[3]); o.z = pk2(x1[0], x1[1]); o.w = pk2(x1[2], x1[3]);
;                     if (wxb) ST_OUT2((u32x4*)(XB + off), o);
;                     ss += x0[0] * x0[0] + x0[1] * x0[1] + x0[2] * x0[2] + x0[3] * x0[3] + x1[0] * x1[0] + x1[1] * x1[1] + x1[2] * x1[2] + x1[3] * x1[3];
;                 }
;                 ss += __shfl_xor(ss, 16); ss += __shfl_xor(ss, 32);
;                 if (fq == 0) atomicAdd(rssn + row, (unsigned long long)(ss * 16777216.f));
;             }
	v_pk_fma_f32 v[36:37], v[36:37], 0.5, v[230:231] op_sel_hi:[1,0,1]
	v_pk_fma_f32 v[38:39], v[38:39], 0.5, v[232:233] op_sel_hi:[1,0,1]
	v_pk_fma_f32 v[32:33], v[32:33], 0.5, v[234:235] op_sel_hi:[1,0,1]
	v_pk_fma_f32 v[34:35], v[34:35], 0.5, v[236:237] op_sel_hi:[1,0,1]
	s_mov_b32 s100, 0x120000
	v_lshl_add_u64 v[182:183], v[196:197], 0, s[100:101]
	global_store_dwordx4 v[182:183], v[36:39], off offset:512
	global_store_dwordx4 v[182:183], v[32:35], off offset:528
	v_cvt_pk_bf16_f32 v186, v36, v37
	v_cvt_pk_bf16_f32 v187, v38, v39
	v_cvt_pk_bf16_f32 v188, v32, v33
	v_cvt_pk_bf16_f32 v189, v34, v35
	s_mov_b32 s100, 0x90000
	v_lshl_add_u64 v[184:185], v[198:199], 0, s[100:101]
	global_store_dwordx4 v[184:185], v[186:189], off offset:256
	v_mul_f32_e32 v171, v37, v37
	v_fmac_f32_e32 v171, v36, v36
	v_fmac_f32_e32 v171, v38, v38
	v_fmac_f32_e32 v171, v39, v39
	v_fmac_f32_e32 v171, v32, v32
	v_fmac_f32_e32 v171, v33, v33
	v_fmac_f32_e32 v171, v34, v34
	v_fmac_f32_e32 v171, v35, v35
	v_add_f32_e32 v170, v170, v171
	ds_bpermute_b32 v163, v202, v170
	s_waitcnt lgkmcnt(0)
	v_add_f32_e32 v170, v170, v163
	ds_bpermute_b32 v163, v203, v170
	s_and_saveexec_b64 s[54:55], s[38:39]
	s_waitcnt lgkmcnt(0)
	v_add_f32_e32 v170, v170, v163
	v_mul_f32_e32 v170, 0x4b800000, v170
	v_trunc_f32_e32 v170, v170
	v_mul_f32_e32 v163, 0x2f800000, v170
	v_floor_f32_e32 v163, v163
	v_fmac_f32_e32 v170, 0xcf800000, v163
	v_cvt_u32_f32_e32 v172, v170
	v_cvt_u32_f32_e32 v173, v163
	s_mov_b32 s100, 0x480
	v_lshl_add_u64 v[184:185], v[200:201], 0, s[100:101]
	global_atomic_add_x2 v[184:185], v[172:173], off
	s_or_b64 exec, exec, s[54:55]
	s_mov_b32 s100, 0x160000
	v_lshl_add_u64 v[204:205], v[194:195], 0, s[100:101]
	global_load_dwordx4 v[230:233], v[204:205], off offset:512
	global_load_dwordx4 v[234:237], v[204:205], off offset:528
	s_waitcnt vmcnt(6)
	v_pk_fma_f32 v[28:29], v[28:29], 0.5, v[206:207] op_sel_hi:[1,0,1]
	v_pk_fma_f32 v[30:31], v[30:31], 0.5, v[208:209] op_sel_hi:[1,0,1]
	v_pk_fma_f32 v[24:25], v[24:25], 0.5, v[210:211] op_sel_hi:[1,0,1]
	v_pk_fma_f32 v[26:27], v[26:27], 0.5, v[212:213] op_sel_hi:[1,0,1]
	s_mov_b32 s100, 0x140000
	v_lshl_add_u64 v[182:183], v[196:197], 0, s[100:101]
	global_store_dwordx4 v[182:183], v[28:31], off
	global_store_dwordx4 v[182:183], v[24:27], off offset:16
	v_cvt_pk_bf16_f32 v186, v28, v29
	v_cvt_pk_bf16_f32 v187, v30, v31
	v_cvt_pk_bf16_f32 v188, v24, v25
	v_cvt_pk_bf16_f32 v189, v26, v27
	s_mov_b32 s100, 0xa0000
	v_lshl_add_u64 v[184:185], v[198:199], 0, s[100:101]
	global_store_dwordx4 v[184:185], v[186:189], off
	v_mul_f32_e32 v170, v29, v29
	v_fmac_f32_e32 v170, v28, v28
	v_fmac_f32_e32 v170, v30, v30
	v_fmac_f32_e32 v170, v31, v31
	v_fmac_f32_e32 v170, v24, v24
	v_fmac_f32_e32 v170, v25, v25
	v_fmac_f32_e32 v170, v26, v26
	v_fmac_f32_e32 v170, v27, v27
	s_waitcnt vmcnt(4)
	v_pk_fma_f32 v[20:21], v[20:21], 0.5, v[214:215] op_sel_hi:[1,0,1]
	v_pk_fma_f32 v[22:23], v[22:23], 0.5, v[216:217] op_sel_hi:[1,0,1]
	v_pk_fma_f32 v[16:17], v[16:17], 0.5, v[218:219] op_sel_hi:[1,0,1]
	v_pk_fma_f32 v[18:19], v[18:19], 0.5, v[220:221] op_sel_hi:[1,0,1]
	s_mov_b32 s100, 0x140000
	v_lshl_add_u64 v[182:183], v[196:197], 0, s[100:101]
	global_store_dwordx4 v[182:183], v[20:23], off offset:512
	global_store_dwordx4 v[182:183], v[16:19], off offset:528
	v_cvt_pk_bf16_f32 v186, v20, v21
	v_cvt_pk_bf16_f32 v187, v22, v23
	v_cvt_pk_bf16_f32 v188, v16, v17
	v_cvt_pk_bf16_f32 v189, v18, v19
	s_mov_b32 s100, 0xa0000
	v_lshl_add_u64 v[184:185], v[198:199], 0, s[100:101]
	global_store_dwordx4 v[184:185], v[186:189], off offset:256
	v_mul_f32_e32 v171, v21, v21
	v_fmac_f32_e32 v171, v20, v20
	v_fmac_f32_e32 v171, v22, v22
	v_fmac_f32_e32 v171, v23, v23
	v_fmac_f32_e32 v171, v16, v16
	v_fmac_f32_e32 v171, v17, v17
	v_fmac_f32_e32 v171, v18, v18
	v_fmac_f32_e32 v171, v19, v19
	v_add_f32_e32 v170, v170, v171
	ds_bpermute_b32 v163, v202, v170
	s_waitcnt lgkmcnt(0)
	v_add_f32_e32 v170, v170, v163
	ds_bpermute_b32 v163, v203, v170
	s_and_saveexec_b64 s[54:55], s[38:39]
	s_waitcnt lgkmcnt(0)
	v_add_f32_e32 v170, v170, v163
	v_mul_f32_e32 v170, 0x4b800000, v170
	v_trunc_f32_e32 v170, v170
	v_mul_f32_e32 v163, 0x2f800000, v170
	v_floor_f32_e32 v163, v163
	v_fmac_f32_e32 v170, 0xcf800000, v163
	v_cvt_u32_f32_e32 v172, v170
	v_cvt_u32_f32_e32 v173, v163
	s_mov_b32 s100, 0x500
	v_lshl_add_u64 v[184:185], v[200:201], 0, s[100:101]
	global_atomic_add_x2 v[184:185], v[172:173], off
	s_or_b64 exec, exec, s[54:55]
	s_waitcnt vmcnt(2)
	v_pk_fma_f32 v[12:13], v[12:13], 0.5, v[222:223] op_sel_hi:[1,0,1]
	v_pk_fma_f32 v[14:15], v[14:15], 0.5, v[224:225] op_sel_hi:[1,0,1]
	v_pk_fma_f32 v[8:9], v[8:9], 0.5, v[226:227] op_sel_hi:[1,0,1]
	v_pk_fma_f32 v[10:11], v[10:11], 0.5, v[228:229] op_sel_hi:[1,0,1]
	s_mov_b32 s100, 0x160000
	v_lshl_add_u64 v[182:183], v[196:197], 0, s[100:101]
	global_store_dwordx4 v[182:183], v[12:15], off
	global_store_dwordx4 v[182:183], v[8:11], off offset:16
	v_cvt_pk_bf16_f32 v186, v12, v13
	v_cvt_pk_bf16_f32 v187, v14, v15
	v_cvt_pk_bf16_f32 v188, v8, v9
	v_cvt_pk_bf16_f32 v189, v10, v11
	s_mov_b32 s100, 0xb0000
	v_lshl_add_u64 v[184:185], v[198:199], 0, s[100:101]
	global_store_dwordx4 v[184:185], v[186:189], off
	v_mul_f32_e32 v170, v13, v13
	v_fmac_f32_e32 v170, v12, v12
	v_fmac_f32_e32 v170, v14, v14
	v_fmac_f32_e32 v170, v15, v15
	v_fmac_f32_e32 v170, v8, v8
	v_fmac_f32_e32 v170, v9, v9
	v_fmac_f32_e32 v170, v10, v10
	v_fmac_f32_e32 v170, v11, v11
	s_waitcnt vmcnt(0)
; __device__ __forceinline__ unsigned pk2(float lo, float hi) { const f32v2_t v = {lo, hi}; const bf16v2_t b = __builtin_convertvector(v, bf16v2_t); return __builtin_bit_cast(unsigned, b); }
; #define ST_OUT2(p, v) __builtin_nontemporal_store((v), (p))
;     __device__ __forceinline__ void operator()(AccRef acc, const Unit& u, int wr, int wc, int fr, int fq) const {
;     ...
;                 const int row = row0 + ai * HALF + m * 16;
;                 float ss = 0.f;
; #pragma unroll
;                 for (int bj = 0; bj < 2; ++bj) {
;                     const size_t off = (size_t)row * DM + col0 + bj * HALF;
;                     f32x4 x0 = *(const f32x4*)(xin + off), x1 = *(const f32x4*)(xin + off + 4);
;                     x0 = x0 + acc[ai][bj][m][0] * scale; x1 = x1 + acc[ai][bj][m][1] * scale;
;                     ST_OUT2((f32x4*)(xout + off), x0); ST_OUT2((f32x4*)(xout + off + 4), x1);
;                     u32x4 o; o.x = pk2(x0[0], x0[1]); o.y = pk2(x0[2], x0[3]); o.z = pk2(x1[0], x1[1]); o.w = pk2(x1[2], x1[3]);
;                     if (wxb) ST_OUT2((u32x4*)(XB + off), o);
;                     ss += x0[0] * x0[0] + x0[1] * x0[1] + x0[2] * x0[2] + x0[3] * x0[3] + x1[0] * x1[0] + x1[1] * x1[1] + x1[2] * x1[2] + x1[3] * x1[3];
;                 }
;                 ss += __shfl_xor(ss, 16); ss += __shfl_xor(ss, 32);
;                 if (fq == 0) atomicAdd(rssn + row, (unsigned long long)(ss * 16777216.f));
;             }
	v_pk_fma_f32 v[4:5], v[4:5], 0.5, v[230:231] op_sel_hi:[1,0,1]
	v_pk_fma_f32 v[6:7], v[6:7], 0.5, v[232:233] op_sel_hi:[1,0,1]
	v_pk_fma_f32 v[0:1], v[0:1], 0.5, v[234:235] op_sel_hi:[1,0,1]
	v_pk_fma_f32 v[2:3], v[2:3], 0.5, v[236:237] op_sel_hi:[1,0,1]
	s_mov_b32 s100, 0x160000
	v_lshl_add_u64 v[182:183], v[196:197], 0, s[100:101]
	global_store_dwordx4 v[182:183], v[4:7], off offset:512
	global_store_dwordx4 v[182:183], v[0:3], off offset:528
	v_cvt_pk_bf16_f32 v186, v4, v5
	v_cvt_pk_bf16_f32 v187, v6, v7
	v_cvt_pk_bf16_f32 v188, v0, v1
	v_cvt_pk_bf16_f32 v189, v2, v3
	s_mov_b32 s100, 0xb0000
	v_lshl_add_u64 v[184:185], v[198:199], 0, s[100:101]
	global_store_dwordx4 v[184:185], v[186:189], off offset:256
	v_mul_f32_e32 v171, v5, v5
	v_fmac_f32_e32 v171, v4, v4
	v_fmac_f32_e32 v171, v6, v6
	v_fmac_f32_e32 v171, v7, v7
	v_fmac_f32_e32 v171, v0, v0
	v_fmac_f32_e32 v171, v1, v1
	v_fmac_f32_e32 v171, v2, v2
	v_fmac_f32_e32 v171, v3, v3
	v_add_f32_e32 v170, v170, v171
	ds_bpermute_b32 v163, v202, v170
	s_waitcnt lgkmcnt(0)
	v_add_f32_e32 v170, v170, v163
	ds_bpermute_b32 v163, v203, v170
	s_and_saveexec_b64 s[54:55], s[38:39]
	s_waitcnt lgkmcnt(0)
	v_add_f32_e32 v170, v170, v163
	v_mul_f32_e32 v170, 0x4b800000, v170
	v_trunc_f32_e32 v170, v170
	v_mul_f32_e32 v163, 0x2f800000, v170
	v_floor_f32_e32 v163, v163
	v_fmac_f32_e32 v170, 0xcf800000, v163
	v_cvt_u32_f32_e32 v172, v170
	v_cvt_u32_f32_e32 v173, v163
	s_mov_b32 s100, 0x580
	v_lshl_add_u64 v[184:185], v[200:201], 0, s[100:101]
	global_atomic_add_x2 v[184:185], v[172:173], off
	s_or_b64 exec, exec, s[54:55]
	s_branch .Lrs2_done
.Lrs2_nowxb:
	s_mov_b32 s100, 0x0
	v_lshl_add_u64 v[204:205], v[194:195], 0, s[100:101]
	global_load_dwordx4 v[206:209], v[204:205], off
	global_load_dwordx4 v[210:213], v[204:205], off offset:16
	s_mov_b32 s100, 0x0
	v_lshl_add_u64 v[204:205], v[194:195], 0, s[100:101]
	global_load_dwordx4 v[214:217], v[204:205], off offset:512
	global_load_dwordx4 v[218:221], v[204:205], off offset:528
	s_mov_b32 s100, 0x20000
	v_lshl_add_u64 v[204:205], v[194:195], 0, s[100:101]
	global_load_dwordx4 v[222:225], v[204:205], off
	global_load_dwordx4 v[226:229], v[204:205], off offset:16
	s_mov_b32 s100, 0x20000
	v_lshl_add_u64 v[204:205], v[194:195], 0, s[100:101]
	global_load_dwordx4 v[230:233], v[204:205], off offset:512
	global_load_dwordx4 v[234:237], v[204:205], off offset:528
	s_waitcnt vmcnt(6)
	v_pk_fma_f32 v[124:125], v[124:125], 0.5, v[206:207] op_sel_hi:[1,0,1]
	v_pk_fma_f32 v[126:127], v[126:127], 0.5, v[208:209] op_sel_hi:[1,0,1]
	v_pk_fma_f32 v[120:121], v[120:121], 0.5, v[210:211] op_sel_hi:[1,0,1]
	v_pk_fma_f32 v[122:123], v[122:123], 0.5, v[212:213] op_sel_hi:[1,0,1]
	s_mov_b32 s100, 0x0
	v_lshl_add_u64 v[182:183], v[196:197], 0, s[100:101]
	global_store_dwordx4 v[182:183], v[124:127], off
	global_store_dwordx4 v[182:183], v[120:123], off offset:16
	v_mul_f32_e32 v170, v125, v125
	v_fmac_f32_e32 v170, v124, v124
	v_fmac_f32_e32 v170, v126, v126
	v_fmac_f32_e32 v170, v127, v127
	v_fmac_f32_e32 v170, v120, v120
	v_fmac_f32_e32 v170, v121, v121
	v_fmac_f32_e32 v170, v122, v122
	v_fmac_f32_e32 v170, v123, v123
	s_mov_b32 s100, 0x40000
	v_lshl_add_u64 v[204:205], v[194:195], 0, s[100:101]
	global_load_dwordx4 v[206:209], v[204:205], off
	global_load_dwordx4 v[210:213], v[204:205], off offset:16
	s_waitcnt vmcnt(6)
	v_pk_fma_f32 v[116:117], v[116:117], 0.5, v[214:215] op_sel_hi:[1,0,1]
	v_pk_fma_f32 v[118:119], v[118:119], 0.5, v[216:217] op_sel_hi:[1,0,1]
	v_pk_fma_f32 v[112:113], v[112:113], 0.5, v[218:219] op_sel_hi:[1,0,1]
	v_pk_fma_f32 v[114:115], v[114:115], 0.5, v[220:221] op_sel_hi:[1,0,1]
	s_mov_b32 s100, 0x0
	v_lshl_add_u64 v[182:183], v[196:197], 0, s[100:101]
	global_store_dwordx4 v[182:183], v[116:119], off offset:512
	global_store_dwordx4 v[182:183], v[112:115], off offset:528
	v_mul_f32_e32 v171, v117, v117
	v_fmac_f32_e32 v171, v116, v116
	v_fmac_f32_e32 v171, v118, v118
	v_fmac_f32_e32 v171, v119, v119
	v_fmac_f32_e32 v171, v112, v112
	v_fmac_f32_e32 v171, v113, v113
	v_fmac_f32_e32 v171, v114, v114
	v_fmac_f32_e32 v171, v115, v115
	v_add_f32_e32 v170, v170, v171
	ds_bpermute_b32 v163, v202, v170
	s_waitcnt lgkmcnt(0)
	v_add_f32_e32 v170, v170, v163
	ds_bpermute_b32 v163, v203, v170
	s_and_saveexec_b64 s[54:55], s[38:39]
	s_waitcnt lgkmcnt(0)
	v_add_f32_e32 v170, v170, v163
	v_mul_f32_e32 v170, 0x4b800000, v170
	v_trunc_f32_e32 v170, v170
	v_mul_f32_e32 v163, 0x2f800000, v170
	v_floor_f32_e32 v163, v163
	v_fmac_f32_e32 v170, 0xcf800000, v163
	v_cvt_u32_f32_e32 v172, v170
	v_cvt_u32_f32_e32 v173, v163
	s_mov_b32 s100, 0x0
	v_lshl_add_u64 v[184:185], v[200:201], 0, s[100:101]
	global_atomic_add_x2 v[184:185], v[172:173], off
	s_or_b64 exec, exec, s[54:55]
	s_mov_b32 s100, 0x40000
	v_lshl_add_u64 v[204:205], v[194:195], 0, s[100:101]
	global_load_dwordx4 v[214:217], v[204:205], off offset:512
	global_load_dwordx4 v[218:221], v[204:205], off offset:528
	s_waitcnt vmcnt(6)
	v_pk_fma_f32 v[108:109], v[108:109], 0.5, v[222:223] op_sel_hi:[1,0,1]
	v_pk_fma_f32 v[110:111], v[110:111], 0.5, v[224:225] op_sel_hi:[1,0,1]
	v_pk_fma_f32 v[104:105], v[104:105], 0.5, v[226:227] op_sel_hi:[1,0,1]
	v_pk_fma_f32 v[106:107], v[106:107], 0.5, v[228:229] op_sel_hi:[1,0,1]
	s_mov_b32 s100, 0x20000
	v_lshl_add_u64 v[182:183], v[196:197], 0, s[100:101]
	global_store_dwordx4 v[182:183], v[108:111], off
	global_store_dwordx4 v[182:183], v[104:107], off offset:16
	v_mul_f32_e32 v170, v109, v109
	v_fmac_f32_e32 v170, v108, v108
	v_fmac_f32_e32 v170, v110, v110
	v_fmac_f32_e32 v170, v111, v111
	v_fmac_f32_e32 v170, v104, v104
	v_fmac_f32_e32 v170, v105, v105
	v_fmac_f32_e32 v170, v106, v106
	v_fmac_f32_e32 v170, v107, v107
	s_mov_b32 s100, 0x60000
	v_lshl_add_u64 v[204:205], v[194:195], 0, s[100:101]
	global_load_dwordx4 v[222:225], v[204:205], off
	global_load_dwordx4 v[226:229], v[204:205], off offset:16
	s_waitcnt vmcnt(6)
; __device__ __forceinline__ unsigned pk2(float lo, float hi) { const f32v2_t v = {lo, hi}; const bf16v2_t b = __builtin_convertvector(v, bf16v2_t); return __builtin_bit_cast(unsigned, b); }
; #define ST_OUT2(p, v) __builtin_nontemporal_store((v), (p))
;     __device__ __forceinline__ void operator()(AccRef acc, const Unit& u, int wr, int wc, int fr, int fq) const {
;     ...
;                 const int row = row0 + ai * HALF + m * 16;
;                 float ss = 0.f;
; #pragma unroll
;                 for (int bj = 0; bj < 2; ++bj) {
;                     const size_t off = (size_t)row * DM + col0 + bj * HALF;
;                     f32x4 x0 = *(const f32x4*)(xin + off), x1 = *(const f32x4*)(xin + off + 4);
;                     x0 = x0 + acc[ai][bj][m][0] * scale; x1 = x1 + acc[ai][bj][m][1] * scale;
;                     ST_OUT2((f32x4*)(xout + off), x0); ST_OUT2((f32x4*)(xout + off + 4), x1);
;                     u32x4 o; o.x = pk2(x0[0], x0[1]); o.y = pk2(x0[2], x0[3]); o.z = pk2(x1[0], x1[1]); o.w = pk2(x1[2], x1[3]);
;                     if (wxb) ST_OUT2((u32x4*)(XB + off), o);
;                     ss += x0[0] * x0[0] + x0[1] * x0[1] + x0[2] * x0[2] + x0[3] * x0[3] + x1[0] * x1[0] + x1[1] * x1[1] + x1[2] * x1[2] + x1[3] * x1[3];
;                 }
;                 ss += __shfl_xor(ss, 16); ss += __shfl_xor(ss, 32);
;                 if (fq == 0) atomicAdd(rssn + row, (unsigned long long)(ss * 16777216.f));
;             }
	v_pk_fma_f32 v[100:101], v[100:101], 0.5, v[230:231] op_sel_hi:[1,0,1]
	v_pk_fma_f32 v[102:103], v[102:103], 0.5, v[232:233] op_sel_hi:[1,0,1]
	v_pk_fma_f32 v[96:97], v[96:97], 0.5, v[234:235] op_sel_hi:[1,0,1]
	v_pk_fma_f32 v[98:99], v[98:99], 0.5, v[236:237] op_sel_hi:[1,0,1]
	s_mov_b32 s100, 0x20000
	v_lshl_add_u64 v[182:183], v[196:197], 0, s[100:101]
	global_store_dwordx4 v[182:183], v[100:103], off offset:512
	global_store_dwordx4 v[182:183], v[96:99], off offset:528
	v_mul_f32_e32 v171, v101, v101
	v_fmac_f32_e32 v171, v100, v100
	v_fmac_f32_e32 v171, v102, v102
	v_fmac_f32_e32 v171, v103, v103
	v_fmac_f32_e32 v171, v96, v96
	v_fmac_f32_e32 v171, v97, v97
	v_fmac_f32_e32 v171, v98, v98
	v_fmac_f32_e32 v171, v99, v99
	v_add_f32_e32 v170, v170, v171
	ds_bpermute_b32 v163, v202, v170
	s_waitcnt lgkmcnt(0)
	v_add_f32_e32 v170, v170, v163
	ds_bpermute_b32 v163, v203, v170
	s_and_saveexec_b64 s[54:55], s[38:39]
	s_waitcnt lgkmcnt(0)
	v_add_f32_e32 v170, v170, v163
	v_mul_f32_e32 v170, 0x4b800000, v170
	v_trunc_f32_e32 v170, v170
	v_mul_f32_e32 v163, 0x2f800000, v170
	v_floor_f32_e32 v163, v163
	v_fmac_f32_e32 v170, 0xcf800000, v163
	v_cvt_u32_f32_e32 v172, v170
	v_cvt_u32_f32_e32 v173, v163
	s_mov_b32 s100, 0x80
	v_lshl_add_u64 v[184:185], v[200:201], 0, s[100:101]
	global_atomic_add_x2 v[184:185], v[172:173], off
	s_or_b64 exec, exec, s[54:55]
	s_mov_b32 s100, 0x60000
	v_lshl_add_u64 v[204:205], v[194:195], 0, s[100:101]
	global_load_dwordx4 v[230:233], v[204:205], off offset:512
	global_load_dwordx4 v[234:237], v[204:205], off offset:528
	s_waitcnt vmcnt(6)
	v_pk_fma_f32 v[92:93], v[92:93], 0.5, v[206:207] op_sel_hi:[1,0,1]
	v_pk_fma_f32 v[94:95], v[94:95], 0.5, v[208:209] op_sel_hi:[1,0,1]
	v_pk_fma_f32 v[88:89], v[88:89], 0.5, v[210:211] op_sel_hi:[1,0,1]
	v_pk_fma_f32 v[90:91], v[90:91], 0.5, v[212:213] op_sel_hi:[1,0,1]
	s_mov_b32 s100, 0x40000
	v_lshl_add_u64 v[182:183], v[196:197], 0, s[100:101]
	global_store_dwordx4 v[182:183], v[92:95], off
	global_store_dwordx4 v[182:183], v[88:91], off offset:16
	v_mul_f32_e32 v170, v93, v93
	v_fmac_f32_e32 v170, v92, v92
	v_fmac_f32_e32 v170, v94, v94
	v_fmac_f32_e32 v170, v95, v95
	v_fmac_f32_e32 v170, v88, v88
	v_fmac_f32_e32 v170, v89, v89
	v_fmac_f32_e32 v170, v90, v90
	v_fmac_f32_e32 v170, v91, v91
	s_mov_b32 s100, 0x100000
	v_lshl_add_u64 v[204:205], v[194:195], 0, s[100:101]
	global_load_dwordx4 v[206:209], v[204:205], off
	global_load_dwordx4 v[210:213], v[204:205], off offset:16
	s_waitcnt vmcnt(6)
	v_pk_fma_f32 v[84:85], v[84:85], 0.5, v[214:215] op_sel_hi:[1,0,1]
	v_pk_fma_f32 v[86:87], v[86:87], 0.5, v[216:217] op_sel_hi:[1,0,1]
	v_pk_fma_f32 v[80:81], v[80:81], 0.5, v[218:219] op_sel_hi:[1,0,1]
	v_pk_fma_f32 v[82:83], v[82:83], 0.5, v[220:221] op_sel_hi:[1,0,1]
	s_mov_b32 s100, 0x40000
	v_lshl_add_u64 v[182:183], v[196:197], 0, s[100:101]
	global_store_dwordx4 v[182:183], v[84:87], off offset:512
	global_store_dwordx4 v[182:183], v[80:83], off offset:528
	v_mul_f32_e32 v171, v85, v85
	v_fmac_f32_e32 v171, v84, v84
	v_fmac_f32_e32 v171, v86, v86
	v_fmac_f32_e32 v171, v87, v87
	v_fmac_f32_e32 v171, v80, v80
	v_fmac_f32_e32 v171, v81, v81
	v_fmac_f32_e32 v171, v82, v82
	v_fmac_f32_e32 v171, v83, v83
	v_add_f32_e32 v170, v170, v171
	ds_bpermute_b32 v163, v202, v170
	s_waitcnt lgkmcnt(0)
	v_add_f32_e32 v170, v170, v163
	ds_bpermute_b32 v163, v203, v170
	s_and_saveexec_b64 s[54:55], s[38:39]
	s_waitcnt lgkmcnt(0)
	v_add_f32_e32 v170, v170, v163
	v_mul_f32_e32 v170, 0x4b800000, v170
	v_trunc_f32_e32 v170, v170
	v_mul_f32_e32 v163, 0x2f800000, v170
	v_floor_f32_e32 v163, v163
	v_fmac_f32_e32 v170, 0xcf800000, v163
	v_cvt_u32_f32_e32 v172, v170
	v_cvt_u32_f32_e32 v173, v163
	s_mov_b32 s100, 0x100
	v_lshl_add_u64 v[184:185], v[200:201], 0, s[100:101]
	global_atomic_add_x2 v[184:185], v[172:173], off
	s_or_b64 exec, exec, s[54:55]
	s_mov_b32 s100, 0x100000
	v_lshl_add_u64 v[204:205], v[194:195], 0, s[100:101]
	global_load_dwordx4 v[214:217], v[204:205], off offset:512
	global_load_dwordx4 v[218:221], v[204:205], off offset:528
	s_waitcnt vmcnt(6)
	v_pk_fma_f32 v[76:77], v[76:77], 0.5, v[222:223] op_sel_hi:[1,0,1]
	v_pk_fma_f32 v[78:79], v[78:79], 0.5, v[224:225] op_sel_hi:[1,0,1]
	v_pk_fma_f32 v[72:73], v[72:73], 0.5, v[226:227] op_sel_hi:[1,0,1]
	v_pk_fma_f32 v[74:75], v[74:75], 0.5, v[228:229] op_sel_hi:[1,0,1]
	s_mov_b32 s100, 0x60000
	v_lshl_add_u64 v[182:183], v[196:197], 0, s[100:101]
	global_store_dwordx4 v[182:183], v[76:79], off
	global_store_dwordx4 v[182:183], v[72:75], off offset:16
	v_mul_f32_e32 v170, v77, v77
	v_fmac_f32_e32 v170, v76, v76
	v_fmac_f32_e32 v170, v78, v78
	v_fmac_f32_e32 v170, v79, v79
	v_fmac_f32_e32 v170, v72, v72
	v_fmac_f32_e32 v170, v73, v73
	v_fmac_f32_e32 v170, v74, v74
	v_fmac_f32_e32 v170, v75, v75
	s_mov_b32 s100, 0x120000
	v_lshl_add_u64 v[204:205], v[194:195], 0, s[100:101]
	global_load_dwordx4 v[222:225], v[204:205], off
	global_load_dwordx4 v[226:229], v[204:205], off offset:16
	s_waitcnt vmcnt(6)
	v_pk_fma_f32 v[68:69], v[68:69], 0.5, v[230:231] op_sel_hi:[1,0,1]
	v_pk_fma_f32 v[70:71], v[70:71], 0.5, v[232:233] op_sel_hi:[1,0,1]
	v_pk_fma_f32 v[64:65], v[64:65], 0.5, v[234:235] op_sel_hi:[1,0,1]
	v_pk_fma_f32 v[66:67], v[66:67], 0.5, v[236:237] op_sel_hi:[1,0,1]
	s_mov_b32 s100, 0x60000
	v_lshl_add_u64 v[182:183], v[196:197], 0, s[100:101]
	global_store_dwordx4 v[182:183], v[68:71], off offset:512
	global_store_dwordx4 v[182:183], v[64:67], off offset:528
	v_mul_f32_e32 v171, v69, v69
	v_fmac_f32_e32 v171, v68, v68
	v_fmac_f32_e32 v171, v70, v70
	v_fmac_f32_e32 v171, v71, v71
	v_fmac_f32_e32 v171, v64, v64
	v_fmac_f32_e32 v171, v65, v65
	v_fmac_f32_e32 v171, v66, v66
	v_fmac_f32_e32 v171, v67, v67
	v_add_f32_e32 v170, v170, v171
	ds_bpermute_b32 v163, v202, v170
	s_waitcnt lgkmcnt(0)
; __device__ __forceinline__ unsigned pk2(float lo, float hi) { const f32v2_t v = {lo, hi}; const bf16v2_t b = __builtin_convertvector(v, bf16v2_t); return __builtin_bit_cast(unsigned, b); }
; #define ST_OUT2(p, v) __builtin_nontemporal_store((v), (p))
;     __device__ __forceinline__ void operator()(AccRef acc, const Unit& u, int wr, int wc, int fr, int fq) const {
;     ...
;                 const int row = row0 + ai * HALF + m * 16;
;                 float ss = 0.f;
; #pragma unroll
;                 for (int bj = 0; bj < 2; ++bj) {
;                     const size_t off = (size_t)row * DM + col0 + bj * HALF;
;                     f32x4 x0 = *(const f32x4*)(xin + off), x1 = *(const f32x4*)(xin + off + 4);
;                     x0 = x0 + acc[ai][bj][m][0] * scale; x1 = x1 + acc[ai][bj][m][1] * scale;
;                     ST_OUT2((f32x4*)(xout + off), x0); ST_OUT2((f32x4*)(xout + off + 4), x1);
;                     u32x4 o; o.x = pk2(x0[0], x0[1]); o.y = pk2(x0[2], x0[3]); o.z = pk2(x1[0], x1[1]); o.w = pk2(x1[2], x1[3]);
;                     if (wxb) ST_OUT2((u32x4*)(XB + off), o);
;                     ss += x0[0] * x0[0] + x0[1] * x0[1] + x0[2] * x0[2] + x0[3] * x0[3] + x1[0] * x1[0] + x1[1] * x1[1] + x1[2] * x1[2] + x1[3] * x1[3];
;                 }
;                 ss += __shfl_xor(ss, 16); ss += __shfl_xor(ss, 32);
;                 if (fq == 0) atomicAdd(rssn + row, (unsigned long long)(ss * 16777216.f));
;             }
	v_add_f32_e32 v170, v170, v163
	ds_bpermute_b32 v163, v203, v170
	s_and_saveexec_b64 s[54:55], s[38:39]
	s_waitcnt lgkmcnt(0)
	v_add_f32_e32 v170, v170, v163
	v_mul_f32_e32 v170, 0x4b800000, v170
	v_trunc_f32_e32 v170, v170
	v_mul_f32_e32 v163, 0x2f800000, v170
	v_floor_f32_e32 v163, v163
	v_fmac_f32_e32 v170, 0xcf800000, v163
	v_cvt_u32_f32_e32 v172, v170
	v_cvt_u32_f32_e32 v173, v163
	s_mov_b32 s100, 0x180
	v_lshl_add_u64 v[184:185], v[200:201], 0, s[100:101]
	global_atomic_add_x2 v[184:185], v[172:173], off
	s_or_b64 exec, exec, s[54:55]
	s_mov_b32 s100, 0x120000
	v_lshl_add_u64 v[204:205], v[194:195], 0, s[100:101]
	global_load_dwordx4 v[230:233], v[204:205], off offset:512
	global_load_dwordx4 v[234:237], v[204:205], off offset:528
	s_waitcnt vmcnt(6)
	v_pk_fma_f32 v[60:61], v[60:61], 0.5, v[206:207] op_sel_hi:[1,0,1]
	v_pk_fma_f32 v[62:63], v[62:63], 0.5, v[208:209] op_sel_hi:[1,0,1]
	v_pk_fma_f32 v[56:57], v[56:57], 0.5, v[210:211] op_sel_hi:[1,0,1]
	v_pk_fma_f32 v[58:59], v[58:59], 0.5, v[212:213] op_sel_hi:[1,0,1]
	s_mov_b32 s100, 0x100000
	v_lshl_add_u64 v[182:183], v[196:197], 0, s[100:101]
	global_store_dwordx4 v[182:183], v[60:63], off
	global_store_dwordx4 v[182:183], v[56:59], off offset:16
	v_mul_f32_e32 v170, v61, v61
	v_fmac_f32_e32 v170, v60, v60
	v_fmac_f32_e32 v170, v62, v62
	v_fmac_f32_e32 v170, v63, v63
	v_fmac_f32_e32 v170, v56, v56
	v_fmac_f32_e32 v170, v57, v57
	v_fmac_f32_e32 v170, v58, v58
	v_fmac_f32_e32 v170, v59, v59
	s_mov_b32 s100, 0x140000
	v_lshl_add_u64 v[204:205], v[194:195], 0, s[100:101]
	global_load_dwordx4 v[206:209], v[204:205], off
	global_load_dwordx4 v[210:213], v[204:205], off offset:16
	s_waitcnt vmcnt(6)
	v_pk_fma_f32 v[52:53], v[52:53], 0.5, v[214:215] op_sel_hi:[1,0,1]
	v_pk_fma_f32 v[54:55], v[54:55], 0.5, v[216:217] op_sel_hi:[1,0,1]
	v_pk_fma_f32 v[48:49], v[48:49], 0.5, v[218:219] op_sel_hi:[1,0,1]
	v_pk_fma_f32 v[50:51], v[50:51], 0.5, v[220:221] op_sel_hi:[1,0,1]
	s_mov_b32 s100, 0x100000
	v_lshl_add_u64 v[182:183], v[196:197], 0, s[100:101]
	global_store_dwordx4 v[182:183], v[52:55], off offset:512
	global_store_dwordx4 v[182:183], v[48:51], off offset:528
	v_mul_f32_e32 v171, v53, v53
	v_fmac_f32_e32 v171, v52, v52
	v_fmac_f32_e32 v171, v54, v54
	v_fmac_f32_e32 v171, v55, v55
	v_fmac_f32_e32 v171, v48, v48
	v_fmac_f32_e32 v171, v49, v49
	v_fmac_f32_e32 v171, v50, v50
	v_fmac_f32_e32 v171, v51, v51
	v_add_f32_e32 v170, v170, v171
	ds_bpermute_b32 v163, v202, v170
	s_waitcnt lgkmcnt(0)
	v_add_f32_e32 v170, v170, v163
	ds_bpermute_b32 v163, v203, v170
	s_and_saveexec_b64 s[54:55], s[38:39]
	s_waitcnt lgkmcnt(0)
	v_add_f32_e32 v170, v170, v163
	v_mul_f32_e32 v170, 0x4b800000, v170
	v_trunc_f32_e32 v170, v170
	v_mul_f32_e32 v163, 0x2f800000, v170
	v_floor_f32_e32 v163, v163
	v_fmac_f32_e32 v170, 0xcf800000, v163
	v_cvt_u32_f32_e32 v172, v170
	v_cvt_u32_f32_e32 v173, v163
	s_mov_b32 s100, 0x400
	v_lshl_add_u64 v[184:185], v[200:201], 0, s[100:101]
	global_atomic_add_x2 v[184:185], v[172:173], off
	s_or_b64 exec, exec, s[54:55]
	s_mov_b32 s100, 0x140000
	v_lshl_add_u64 v[204:205], v[194:195], 0, s[100:101]
	global_load_dwordx4 v[214:217], v[204:205], off offset:512
	global_load_dwordx4 v[218:221], v[204:205], off offset:528
	s_waitcnt vmcnt(6)
	v_pk_fma_f32 v[44:45], v[44:45], 0.5, v[222:223] op_sel_hi:[1,0,1]
	v_pk_fma_f32 v[46:47], v[46:47], 0.5, v[224:225] op_sel_hi:[1,0,1]
	v_pk_fma_f32 v[40:41], v[40:41], 0.5, v[226:227] op_sel_hi:[1,0,1]
	v_pk_fma_f32 v[42:43], v[42:43], 0.5, v[228:229] op_sel_hi:[1,0,1]
	s_mov_b32 s100, 0x120000
	v_lshl_add_u64 v[182:183], v[196:197], 0, s[100:101]
	global_store_dwordx4 v[182:183], v[44:47], off
	global_store_dwordx4 v[182:183], v[40:43], off offset:16
	v_mul_f32_e32 v170, v45, v45
	v_fmac_f32_e32 v170, v44, v44
	v_fmac_f32_e32 v170, v46, v46
	v_fmac_f32_e32 v170, v47, v47
	v_fmac_f32_e32 v170, v40, v40
	v_fmac_f32_e32 v170, v41, v41
	v_fmac_f32_e32 v170, v42, v42
	v_fmac_f32_e32 v170, v43, v43
	s_mov_b32 s100, 0x160000
	v_lshl_add_u64 v[204:205], v[194:195], 0, s[100:101]
	global_load_dwordx4 v[222:225], v[204:205], off
	global_load_dwordx4 v[226:229], v[204:205], off offset:16
	s_waitcnt vmcnt(6)
	v_pk_fma_f32 v[36:37], v[36:37], 0.5, v[230:231] op_sel_hi:[1,0,1]
	v_pk_fma_f32 v[38:39], v[38:39], 0.5, v[232:233] op_sel_hi:[1,0,1]
	v_pk_fma_f32 v[32:33], v[32:33], 0.5, v[234:235] op_sel_hi:[1,0,1]
	v_pk_fma_f32 v[34:35], v[34:35], 0.5, v[236:237] op_sel_hi:[1,0,1]
	s_mov_b32 s100, 0x120000
	v_lshl_add_u64 v[182:183], v[196:197], 0, s[100:101]
	global_store_dwordx4 v[182:183], v[36:39], off offset:512
	global_store_dwordx4 v[182:183], v[32:35], off offset:528
	v_mul_f32_e32 v171, v37, v37
	v_fmac_f32_e32 v171, v36, v36
	v_fmac_f32_e32 v171, v38, v38
	v_fmac_f32_e32 v171, v39, v39
	v_fmac_f32_e32 v171, v32, v32
	v_fmac_f32_e32 v171, v33, v33
	v_fmac_f32_e32 v171, v34, v34
	v_fmac_f32_e32 v171, v35, v35
	v_add_f32_e32 v170, v170, v171
	ds_bpermute_b32 v163, v202, v170
	s_waitcnt lgkmcnt(0)
	v_add_f32_e32 v170, v170, v163
	ds_bpermute_b32 v163, v203, v170
	s_and_saveexec_b64 s[54:55], s[38:39]
	s_waitcnt lgkmcnt(0)
; __device__ __forceinline__ unsigned pk2(float lo, float hi) { const f32v2_t v = {lo, hi}; const bf16v2_t b = __builtin_convertvector(v, bf16v2_t); return __builtin_bit_cast(unsigned, b); }
; #define ST_OUT2(p, v) __builtin_nontemporal_store((v), (p))
; #define PG8_BAR __builtin_amdgcn_s_barrier()
; template <class Epi, class Sched>
; __device__ __forceinline__ void gemm_phase(LAS unsigned char* lds, const Gemm g, const Sched& S, const Epi& E) {
;     ...
;         if (!has_next) break;
; #pragma unroll
;         for (int a = 0; a < 2; ++a)
; #pragma unroll
;             for (int b = 0; b < 2; ++b)
; #pragma unroll
;                 for (int m = 0; m < 4; ++m)
; #pragma unroll
;                     for (int n = 0; n < 2; ++n) acc[a][b][m][n] = (f32x4){0.f, 0.f, 0.f, 0.f};
;         cur = nxt; cA = nA; cB = nB; ++ui;
;         if (Sched::SEGMENTED) nt = S.nt(cur);
;     ...
;         if (wr == 1) PG8_BAR;
;     __device__ __forceinline__ void operator()(AccRef acc, const Unit& u, int wr, int wc, int fr, int fq) const {
;     ...
;                 const int row = row0 + ai * HALF + m * 16;
;                 float ss = 0.f;
; #pragma unroll
;                 for (int bj = 0; bj < 2; ++bj) {
;                     const size_t off = (size_t)row * DM + col0 + bj * HALF;
;                     f32x4 x0 = *(const f32x4*)(xin + off), x1 = *(const f32x4*)(xin + off + 4);
;                     x0 = x0 + acc[ai][bj][m][0] * scale; x1 = x1 + acc[ai][bj][m][1] * scale;
;                     ST_OUT2((f32x4*)(xout + off), x0); ST_OUT2((f32x4*)(xout + off + 4), x1);
;                     u32x4 o; o.x = pk2(x0[0], x0[1]); o.y = pk2(x0[2], x0[3]); o.z = pk2(x1[0], x1[1]); o.w = pk2(x1[2], x1[3]);
;                     if (wxb) ST_OUT2((u32x4*)(XB + off), o);
;                     ss += x0[0] * x0[0] + x0[1] * x0[1] + x0[2] * x0[2] + x0[3] * x0[3] + x1[0] * x1[0] + x1[1] * x1[1] + x1[2] * x1[2] + x1[3] * x1[3];
;                 }
;                 ss += __shfl_xor(ss, 16); ss += __shfl_xor(ss, 32);
;                 if (fq == 0) atomicAdd(rssn + row, (unsigned long long)(ss * 16777216.f));
;             }
	v_add_f32_e32 v170, v170, v163
	v_mul_f32_e32 v170, 0x4b800000, v170
	v_trunc_f32_e32 v170, v170
	v_mul_f32_e32 v163, 0x2f800000, v170
	v_floor_f32_e32 v163, v163
	v_fmac_f32_e32 v170, 0xcf800000, v163
	v_cvt_u32_f32_e32 v172, v170
	v_cvt_u32_f32_e32 v173, v163
	s_mov_b32 s100, 0x480
	v_lshl_add_u64 v[184:185], v[200:201], 0, s[100:101]
	global_atomic_add_x2 v[184:185], v[172:173], off
	s_or_b64 exec, exec, s[54:55]
	s_mov_b32 s100, 0x160000
	v_lshl_add_u64 v[204:205], v[194:195], 0, s[100:101]
	global_load_dwordx4 v[230:233], v[204:205], off offset:512
	global_load_dwordx4 v[234:237], v[204:205], off offset:528
	s_waitcnt vmcnt(6)
	v_pk_fma_f32 v[28:29], v[28:29], 0.5, v[206:207] op_sel_hi:[1,0,1]
	v_pk_fma_f32 v[30:31], v[30:31], 0.5, v[208:209] op_sel_hi:[1,0,1]
	v_pk_fma_f32 v[24:25], v[24:25], 0.5, v[210:211] op_sel_hi:[1,0,1]
	v_pk_fma_f32 v[26:27], v[26:27], 0.5, v[212:213] op_sel_hi:[1,0,1]
	s_mov_b32 s100, 0x140000
	v_lshl_add_u64 v[182:183], v[196:197], 0, s[100:101]
	global_store_dwordx4 v[182:183], v[28:31], off
	global_store_dwordx4 v[182:183], v[24:27], off offset:16
	v_mul_f32_e32 v170, v29, v29
	v_fmac_f32_e32 v170, v28, v28
	v_fmac_f32_e32 v170, v30, v30
	v_fmac_f32_e32 v170, v31, v31
	v_fmac_f32_e32 v170, v24, v24
	v_fmac_f32_e32 v170, v25, v25
	v_fmac_f32_e32 v170, v26, v26
	v_fmac_f32_e32 v170, v27, v27
	s_waitcnt vmcnt(4)
	v_pk_fma_f32 v[20:21], v[20:21], 0.5, v[214:215] op_sel_hi:[1,0,1]
	v_pk_fma_f32 v[22:23], v[22:23], 0.5, v[216:217] op_sel_hi:[1,0,1]
	v_pk_fma_f32 v[16:17], v[16:17], 0.5, v[218:219] op_sel_hi:[1,0,1]
	v_pk_fma_f32 v[18:19], v[18:19], 0.5, v[220:221] op_sel_hi:[1,0,1]
	s_mov_b32 s100, 0x140000
	v_lshl_add_u64 v[182:183], v[196:197], 0, s[100:101]
	global_store_dwordx4 v[182:183], v[20:23], off offset:512
	global_store_dwordx4 v[182:183], v[16:19], off offset:528
	v_mul_f32_e32 v171, v21, v21
	v_fmac_f32_e32 v171, v20, v20
	v_fmac_f32_e32 v171, v22, v22
	v_fmac_f32_e32 v171, v23, v23
	v_fmac_f32_e32 v171, v16, v16
	v_fmac_f32_e32 v171, v17, v17
	v_fmac_f32_e32 v171, v18, v18
	v_fmac_f32_e32 v171, v19, v19
	v_add_f32_e32 v170, v170, v171
	ds_bpermute_b32 v163, v202, v170
	s_waitcnt lgkmcnt(0)
	v_add_f32_e32 v170, v170, v163
	ds_bpermute_b32 v163, v203, v170
	s_and_saveexec_b64 s[54:55], s[38:39]
	s_waitcnt lgkmcnt(0)
	v_add_f32_e32 v170, v170, v163
	v_mul_f32_e32 v170, 0x4b800000, v170
	v_trunc_f32_e32 v170, v170
	v_mul_f32_e32 v163, 0x2f800000, v170
	v_floor_f32_e32 v163, v163
	v_fmac_f32_e32 v170, 0xcf800000, v163
	v_cvt_u32_f32_e32 v172, v170
	v_cvt_u32_f32_e32 v173, v163
	s_mov_b32 s100, 0x500
	v_lshl_add_u64 v[184:185], v[200:201], 0, s[100:101]
	global_atomic_add_x2 v[184:185], v[172:173], off
	s_or_b64 exec, exec, s[54:55]
	s_waitcnt vmcnt(2)
	v_pk_fma_f32 v[12:13], v[12:13], 0.5, v[222:223] op_sel_hi:[1,0,1]
	v_pk_fma_f32 v[14:15], v[14:15], 0.5, v[224:225] op_sel_hi:[1,0,1]
	v_pk_fma_f32 v[8:9], v[8:9], 0.5, v[226:227] op_sel_hi:[1,0,1]
	v_pk_fma_f32 v[10:11], v[10:11], 0.5, v[228:229] op_sel_hi:[1,0,1]
	s_mov_b32 s100, 0x160000
	v_lshl_add_u64 v[182:183], v[196:197], 0, s[100:101]
	global_store_dwordx4 v[182:183], v[12:15], off
	global_store_dwordx4 v[182:183], v[8:11], off offset:16
	v_mul_f32_e32 v170, v13, v13
	v_fmac_f32_e32 v170, v12, v12
	v_fmac_f32_e32 v170, v14, v14
	v_fmac_f32_e32 v170, v15, v15
	v_fmac_f32_e32 v170, v8, v8
	v_fmac_f32_e32 v170, v9, v9
	v_fmac_f32_e32 v170, v10, v10
	v_fmac_f32_e32 v170, v11, v11
	s_waitcnt vmcnt(0)
	v_pk_fma_f32 v[4:5], v[4:5], 0.5, v[230:231] op_sel_hi:[1,0,1]
	v_pk_fma_f32 v[6:7], v[6:7], 0.5, v[232:233] op_sel_hi:[1,0,1]
	v_pk_fma_f32 v[0:1], v[0:1], 0.5, v[234:235] op_sel_hi:[1,0,1]
	v_pk_fma_f32 v[2:3], v[2:3], 0.5, v[236:237] op_sel_hi:[1,0,1]
	s_mov_b32 s100, 0x160000
	v_lshl_add_u64 v[182:183], v[196:197], 0, s[100:101]
	global_store_dwordx4 v[182:183], v[4:7], off offset:512
	global_store_dwordx4 v[182:183], v[0:3], off offset:528
	v_mul_f32_e32 v171, v5, v5
	v_fmac_f32_e32 v171, v4, v4
	v_fmac_f32_e32 v171, v6, v6
	v_fmac_f32_e32 v171, v7, v7
	v_fmac_f32_e32 v171, v0, v0
	v_fmac_f32_e32 v171, v1, v1
	v_fmac_f32_e32 v171, v2, v2
	v_fmac_f32_e32 v171, v3, v3
	v_add_f32_e32 v170, v170, v171
	ds_bpermute_b32 v163, v202, v170
	s_waitcnt lgkmcnt(0)
	v_add_f32_e32 v170, v170, v163
	ds_bpermute_b32 v163, v203, v170
	s_and_saveexec_b64 s[54:55], s[38:39]
	s_waitcnt lgkmcnt(0)
	v_add_f32_e32 v170, v170, v163
	v_mul_f32_e32 v170, 0x4b800000, v170
	v_trunc_f32_e32 v170, v170
	v_mul_f32_e32 v163, 0x2f800000, v170
	v_floor_f32_e32 v163, v163
	v_fmac_f32_e32 v170, 0xcf800000, v163
	v_cvt_u32_f32_e32 v172, v170
	v_cvt_u32_f32_e32 v173, v163
	s_mov_b32 s100, 0x580
	v_lshl_add_u64 v[184:185], v[200:201], 0, s[100:101]
	global_atomic_add_x2 v[184:185], v[172:173], off
	s_or_b64 exec, exec, s[54:55]
.Lrs2_done:
	s_mov_b64 s[16:17], 0x58000
	s_mov_b64 s[42:43], exec
	s_and_b64 vcc, exec, s[40:41]
	s_mov_b64 s[40:41], -1
	s_cbranch_vccnz .LBB0_667
	s_andn2_b64 vcc, exec, s[22:23]
	s_cbranch_vccnz .LBB0_666
	s_barrier
	s_branch .LBB0_666
